# v118 without s_setprio toggling in the custom double-tile GEMM loops (0 setprio, as in the hand-scheduled recipe)
# baseline (speedup 1.0000x reference)
.Lg2_k:
	s_waitcnt vmcnt(0)
	s_barrier
	s_add_i32 m0, s58, 0xc000
	s_nop 0
	global_load_lds_dwordx4 v74, s[56:57]
	s_add_i32 m0, s58, 0xd000
	s_nop 0
	global_load_lds_dwordx4 v75, s[56:57]
	s_add_i32 m0, s58, 0xe000
	s_nop 0
	global_load_lds_dwordx4 v76, s[56:57]
	s_add_i32 m0, s58, 0xf000
	s_nop 0
	global_load_lds_dwordx4 v77, s[56:57]
	s_add_u32 s56, s56, 0x80
	s_addc_u32 s57, s57, 0
	ds_read_b128 v[148:151], v78 offset:0
	ds_read_b128 v[152:155], v78 offset:2048
	ds_read_b128 v[156:159], v78 offset:4096
	ds_read_b128 v[160:163], v78 offset:6144
	ds_read_b128 v[188:191], v79 offset:32768
	ds_read_b128 v[192:195], v79 offset:34816
	ds_read_b128 v[208:211], v79 offset:36864
	ds_read_b128 v[212:215], v79 offset:38912
	ds_read_b128 v[164:167], v78 offset:16384
	ds_read_b128 v[168:171], v78 offset:18432
	ds_read_b128 v[174:177], v78 offset:20480
	ds_read_b128 v[182:185], v78 offset:22528
	s_waitcnt lgkmcnt(4)
	v_mfma_f32_16x16x32_bf16 v[62:65], v[188:191], v[148:151], v[62:65]
	v_mfma_f32_16x16x32_bf16 v[58:61], v[192:195], v[148:151], v[58:61]
	v_mfma_f32_16x16x32_bf16 v[54:57], v[208:211], v[148:151], v[54:57]
	v_mfma_f32_16x16x32_bf16 v[50:53], v[212:215], v[148:151], v[50:53]
	v_mfma_f32_16x16x32_bf16 v[46:49], v[188:191], v[152:155], v[46:49]
	v_mfma_f32_16x16x32_bf16 v[42:45], v[192:195], v[152:155], v[42:45]
	v_mfma_f32_16x16x32_bf16 v[38:41], v[208:211], v[152:155], v[38:41]
	v_mfma_f32_16x16x32_bf16 v[34:37], v[212:215], v[152:155], v[34:37]
	v_mfma_f32_16x16x32_bf16 v[30:33], v[188:191], v[156:159], v[30:33]
	v_mfma_f32_16x16x32_bf16 v[26:29], v[192:195], v[156:159], v[26:29]
	v_mfma_f32_16x16x32_bf16 v[22:25], v[208:211], v[156:159], v[22:25]
	v_mfma_f32_16x16x32_bf16 v[18:21], v[212:215], v[156:159], v[18:21]
	v_mfma_f32_16x16x32_bf16 v[14:17], v[188:191], v[160:163], v[14:17]
	v_mfma_f32_16x16x32_bf16 v[10:13], v[192:195], v[160:163], v[10:13]
	v_mfma_f32_16x16x32_bf16 v[6:9], v[208:211], v[160:163], v[6:9]
	v_mfma_f32_16x16x32_bf16 v[2:5], v[212:215], v[160:163], v[2:5]
	s_waitcnt lgkmcnt(0)
	v_mfma_f32_16x16x32_bf16 v[66:69], v[188:191], v[164:167], v[66:69]
	v_mfma_f32_16x16x32_bf16 v[70:73], v[192:195], v[164:167], v[70:73]
	v_mfma_f32_16x16x32_bf16 v[82:85], v[208:211], v[164:167], v[82:85]
	v_mfma_f32_16x16x32_bf16 v[88:91], v[212:215], v[164:167], v[88:91]
	v_mfma_f32_16x16x32_bf16 v[92:95], v[188:191], v[168:171], v[92:95]
	v_mfma_f32_16x16x32_bf16 v[96:99], v[192:195], v[168:171], v[96:99]
	v_mfma_f32_16x16x32_bf16 v[100:103], v[208:211], v[168:171], v[100:103]
	v_mfma_f32_16x16x32_bf16 v[106:109], v[212:215], v[168:171], v[106:109]
	v_mfma_f32_16x16x32_bf16 v[110:113], v[188:191], v[174:177], v[110:113]
	v_mfma_f32_16x16x32_bf16 v[114:117], v[192:195], v[174:177], v[114:117]
	v_mfma_f32_16x16x32_bf16 v[118:121], v[208:211], v[174:177], v[118:121]
	v_mfma_f32_16x16x32_bf16 v[122:125], v[212:215], v[174:177], v[122:125]
	v_mfma_f32_16x16x32_bf16 v[126:129], v[188:191], v[182:185], v[126:129]
	v_mfma_f32_16x16x32_bf16 v[136:139], v[192:195], v[182:185], v[136:139]
	v_mfma_f32_16x16x32_bf16 v[140:143], v[208:211], v[182:185], v[140:143]
	v_mfma_f32_16x16x32_bf16 v[144:147], v[212:215], v[182:185], v[144:147]
	ds_read_b128 v[148:151], v80 offset:0
	ds_read_b128 v[152:155], v80 offset:2048
	ds_read_b128 v[156:159], v80 offset:4096
	ds_read_b128 v[160:163], v80 offset:6144
	ds_read_b128 v[188:191], v81 offset:32768
	ds_read_b128 v[192:195], v81 offset:34816
	ds_read_b128 v[208:211], v81 offset:36864
	ds_read_b128 v[212:215], v81 offset:38912
	ds_read_b128 v[164:167], v80 offset:16384
	ds_read_b128 v[168:171], v80 offset:18432
	ds_read_b128 v[174:177], v80 offset:20480
	ds_read_b128 v[182:185], v80 offset:22528
	s_waitcnt lgkmcnt(0)
	s_barrier
	s_add_i32 m0, s58, 0x0
	s_nop 0
	global_load_lds_dwordx4 v74, s[50:51]
	s_add_i32 m0, s58, 0x1000
	s_nop 0
	global_load_lds_dwordx4 v75, s[50:51]
	s_add_i32 m0, s58, 0x2000
	s_nop 0
	global_load_lds_dwordx4 v76, s[50:51]
	s_add_i32 m0, s58, 0x3000
	s_nop 0
	global_load_lds_dwordx4 v77, s[50:51]
	s_add_i32 m0, s58, 0x4000
	s_nop 0
	global_load_lds_dwordx4 v74, s[52:53]
	s_add_i32 m0, s58, 0x5000
	s_nop 0
	global_load_lds_dwordx4 v75, s[52:53]
	s_add_i32 m0, s58, 0x6000
	s_nop 0
	global_load_lds_dwordx4 v76, s[52:53]
	s_add_i32 m0, s58, 0x7000
	s_nop 0
	global_load_lds_dwordx4 v77, s[52:53]
	s_add_u32 s50, s50, 0x80
	s_addc_u32 s51, s51, 0
	s_add_u32 s52, s52, 0x80
	s_addc_u32 s53, s53, 0
	v_mfma_f32_16x16x32_bf16 v[62:65], v[188:191], v[148:151], v[62:65]
	v_mfma_f32_16x16x32_bf16 v[58:61], v[192:195], v[148:151], v[58:61]
	v_mfma_f32_16x16x32_bf16 v[54:57], v[208:211], v[148:151], v[54:57]
	v_mfma_f32_16x16x32_bf16 v[50:53], v[212:215], v[148:151], v[50:53]
	v_mfma_f32_16x16x32_bf16 v[46:49], v[188:191], v[152:155], v[46:49]
	v_mfma_f32_16x16x32_bf16 v[42:45], v[192:195], v[152:155], v[42:45]
	v_mfma_f32_16x16x32_bf16 v[38:41], v[208:211], v[152:155], v[38:41]
	v_mfma_f32_16x16x32_bf16 v[34:37], v[212:215], v[152:155], v[34:37]
	v_mfma_f32_16x16x32_bf16 v[30:33], v[188:191], v[156:159], v[30:33]
	v_mfma_f32_16x16x32_bf16 v[26:29], v[192:195], v[156:159], v[26:29]
	v_mfma_f32_16x16x32_bf16 v[22:25], v[208:211], v[156:159], v[22:25]
	v_mfma_f32_16x16x32_bf16 v[18:21], v[212:215], v[156:159], v[18:21]
	v_mfma_f32_16x16x32_bf16 v[14:17], v[188:191], v[160:163], v[14:17]
	v_mfma_f32_16x16x32_bf16 v[10:13], v[192:195], v[160:163], v[10:13]
	v_mfma_f32_16x16x32_bf16 v[6:9], v[208:211], v[160:163], v[6:9]
	v_mfma_f32_16x16x32_bf16 v[2:5], v[212:215], v[160:163], v[2:5]
	v_mfma_f32_16x16x32_bf16 v[66:69], v[188:191], v[164:167], v[66:69]
	v_mfma_f32_16x16x32_bf16 v[70:73], v[192:195], v[164:167], v[70:73]
	v_mfma_f32_16x16x32_bf16 v[82:85], v[208:211], v[164:167], v[82:85]
	v_mfma_f32_16x16x32_bf16 v[88:91], v[212:215], v[164:167], v[88:91]
	v_mfma_f32_16x16x32_bf16 v[92:95], v[188:191], v[168:171], v[92:95]
	v_mfma_f32_16x16x32_bf16 v[96:99], v[192:195], v[168:171], v[96:99]
	v_mfma_f32_16x16x32_bf16 v[100:103], v[208:211], v[168:171], v[100:103]
	v_mfma_f32_16x16x32_bf16 v[106:109], v[212:215], v[168:171], v[106:109]
	v_mfma_f32_16x16x32_bf16 v[110:113], v[188:191], v[174:177], v[110:113]
	v_mfma_f32_16x16x32_bf16 v[114:117], v[192:195], v[174:177], v[114:117]
	v_mfma_f32_16x16x32_bf16 v[118:121], v[208:211], v[174:177], v[118:121]
	v_mfma_f32_16x16x32_bf16 v[122:125], v[212:215], v[174:177], v[122:125]
	v_mfma_f32_16x16x32_bf16 v[126:129], v[188:191], v[182:185], v[126:129]
	v_mfma_f32_16x16x32_bf16 v[136:139], v[192:195], v[182:185], v[136:139]
	v_mfma_f32_16x16x32_bf16 v[140:143], v[208:211], v[182:185], v[140:143]
	v_mfma_f32_16x16x32_bf16 v[144:147], v[212:215], v[182:185], v[144:147]
	s_waitcnt vmcnt(0)
	s_barrier
	s_add_i32 m0, s58, 0x8000
	s_nop 0
	global_load_lds_dwordx4 v74, s[56:57]
	s_add_i32 m0, s58, 0x9000
	s_nop 0
	global_load_lds_dwordx4 v75, s[56:57]
	s_add_i32 m0, s58, 0xa000
	s_nop 0
	global_load_lds_dwordx4 v76, s[56:57]
	s_add_i32 m0, s58, 0xb000
	s_nop 0
	global_load_lds_dwordx4 v77, s[56:57]
	s_add_u32 s56, s56, 0x80
	s_addc_u32 s57, s57, 0
	ds_read_b128 v[148:151], v78 offset:0
	ds_read_b128 v[152:155], v78 offset:2048
	ds_read_b128 v[156:159], v78 offset:4096
	ds_read_b128 v[160:163], v78 offset:6144
	ds_read_b128 v[188:191], v79 offset:49152
	ds_read_b128 v[192:195], v79 offset:51200
	ds_read_b128 v[208:211], v79 offset:53248
	ds_read_b128 v[212:215], v79 offset:55296
	ds_read_b128 v[164:167], v78 offset:16384
	ds_read_b128 v[168:171], v78 offset:18432
	ds_read_b128 v[174:177], v78 offset:20480
	ds_read_b128 v[182:185], v78 offset:22528
	s_waitcnt lgkmcnt(4)
	v_mfma_f32_16x16x32_bf16 v[62:65], v[188:191], v[148:151], v[62:65]
	v_mfma_f32_16x16x32_bf16 v[58:61], v[192:195], v[148:151], v[58:61]
	v_mfma_f32_16x16x32_bf16 v[54:57], v[208:211], v[148:151], v[54:57]
	v_mfma_f32_16x16x32_bf16 v[50:53], v[212:215], v[148:151], v[50:53]
	v_mfma_f32_16x16x32_bf16 v[46:49], v[188:191], v[152:155], v[46:49]
	v_mfma_f32_16x16x32_bf16 v[42:45], v[192:195], v[152:155], v[42:45]
	v_mfma_f32_16x16x32_bf16 v[38:41], v[208:211], v[152:155], v[38:41]
	v_mfma_f32_16x16x32_bf16 v[34:37], v[212:215], v[152:155], v[34:37]
	v_mfma_f32_16x16x32_bf16 v[30:33], v[188:191], v[156:159], v[30:33]
	v_mfma_f32_16x16x32_bf16 v[26:29], v[192:195], v[156:159], v[26:29]
	v_mfma_f32_16x16x32_bf16 v[22:25], v[208:211], v[156:159], v[22:25]
	v_mfma_f32_16x16x32_bf16 v[18:21], v[212:215], v[156:159], v[18:21]
	v_mfma_f32_16x16x32_bf16 v[14:17], v[188:191], v[160:163], v[14:17]
	v_mfma_f32_16x16x32_bf16 v[10:13], v[192:195], v[160:163], v[10:13]
	v_mfma_f32_16x16x32_bf16 v[6:9], v[208:211], v[160:163], v[6:9]
	v_mfma_f32_16x16x32_bf16 v[2:5], v[212:215], v[160:163], v[2:5]
	s_waitcnt lgkmcnt(0)
	v_mfma_f32_16x16x32_bf16 v[66:69], v[188:191], v[164:167], v[66:69]
	v_mfma_f32_16x16x32_bf16 v[70:73], v[192:195], v[164:167], v[70:73]
	v_mfma_f32_16x16x32_bf16 v[82:85], v[208:211], v[164:167], v[82:85]
	v_mfma_f32_16x16x32_bf16 v[88:91], v[212:215], v[164:167], v[88:91]
	v_mfma_f32_16x16x32_bf16 v[92:95], v[188:191], v[168:171], v[92:95]
	v_mfma_f32_16x16x32_bf16 v[96:99], v[192:195], v[168:171], v[96:99]
	v_mfma_f32_16x16x32_bf16 v[100:103], v[208:211], v[168:171], v[100:103]
	v_mfma_f32_16x16x32_bf16 v[106:109], v[212:215], v[168:171], v[106:109]
	v_mfma_f32_16x16x32_bf16 v[110:113], v[188:191], v[174:177], v[110:113]
	v_mfma_f32_16x16x32_bf16 v[114:117], v[192:195], v[174:177], v[114:117]
	v_mfma_f32_16x16x32_bf16 v[118:121], v[208:211], v[174:177], v[118:121]
	v_mfma_f32_16x16x32_bf16 v[122:125], v[212:215], v[174:177], v[122:125]
	v_mfma_f32_16x16x32_bf16 v[126:129], v[188:191], v[182:185], v[126:129]
	v_mfma_f32_16x16x32_bf16 v[136:139], v[192:195], v[182:185], v[136:139]
	v_mfma_f32_16x16x32_bf16 v[140:143], v[208:211], v[182:185], v[140:143]
	v_mfma_f32_16x16x32_bf16 v[144:147], v[212:215], v[182:185], v[144:147]
	ds_read_b128 v[148:151], v80 offset:0
	ds_read_b128 v[152:155], v80 offset:2048
	ds_read_b128 v[156:159], v80 offset:4096
	ds_read_b128 v[160:163], v80 offset:6144
	ds_read_b128 v[188:191], v81 offset:49152
	ds_read_b128 v[192:195], v81 offset:51200
	ds_read_b128 v[208:211], v81 offset:53248
	ds_read_b128 v[212:215], v81 offset:55296
	ds_read_b128 v[164:167], v80 offset:16384
	ds_read_b128 v[168:171], v80 offset:18432
	ds_read_b128 v[174:177], v80 offset:20480
	ds_read_b128 v[182:185], v80 offset:22528
	s_waitcnt lgkmcnt(0)
	s_barrier
	s_add_i32 m0, s58, 0x0
	s_nop 0
	global_load_lds_dwordx4 v74, s[50:51]
	s_add_i32 m0, s58, 0x1000
	s_nop 0
	global_load_lds_dwordx4 v75, s[50:51]
	s_add_i32 m0, s58, 0x2000
	s_nop 0
	global_load_lds_dwordx4 v76, s[50:51]
	s_add_i32 m0, s58, 0x3000
	s_nop 0
	global_load_lds_dwordx4 v77, s[50:51]
	s_add_i32 m0, s58, 0x4000
	s_nop 0
	global_load_lds_dwordx4 v74, s[52:53]
	s_add_i32 m0, s58, 0x5000
	s_nop 0
	global_load_lds_dwordx4 v75, s[52:53]
	s_add_i32 m0, s58, 0x6000
	s_nop 0
	global_load_lds_dwordx4 v76, s[52:53]
	s_add_i32 m0, s58, 0x7000
	s_nop 0
	global_load_lds_dwordx4 v77, s[52:53]
	s_add_u32 s50, s50, 0x80
	s_addc_u32 s51, s51, 0
	s_add_u32 s52, s52, 0x80
	s_addc_u32 s53, s53, 0
	v_mfma_f32_16x16x32_bf16 v[62:65], v[188:191], v[148:151], v[62:65]
	v_mfma_f32_16x16x32_bf16 v[58:61], v[192:195], v[148:151], v[58:61]
	v_mfma_f32_16x16x32_bf16 v[54:57], v[208:211], v[148:151], v[54:57]
	v_mfma_f32_16x16x32_bf16 v[50:53], v[212:215], v[148:151], v[50:53]
	v_mfma_f32_16x16x32_bf16 v[46:49], v[188:191], v[152:155], v[46:49]
	v_mfma_f32_16x16x32_bf16 v[42:45], v[192:195], v[152:155], v[42:45]
	v_mfma_f32_16x16x32_bf16 v[38:41], v[208:211], v[152:155], v[38:41]
	v_mfma_f32_16x16x32_bf16 v[34:37], v[212:215], v[152:155], v[34:37]
	v_mfma_f32_16x16x32_bf16 v[30:33], v[188:191], v[156:159], v[30:33]
	v_mfma_f32_16x16x32_bf16 v[26:29], v[192:195], v[156:159], v[26:29]
	v_mfma_f32_16x16x32_bf16 v[22:25], v[208:211], v[156:159], v[22:25]
	v_mfma_f32_16x16x32_bf16 v[18:21], v[212:215], v[156:159], v[18:21]
	v_mfma_f32_16x16x32_bf16 v[14:17], v[188:191], v[160:163], v[14:17]
	v_mfma_f32_16x16x32_bf16 v[10:13], v[192:195], v[160:163], v[10:13]
	v_mfma_f32_16x16x32_bf16 v[6:9], v[208:211], v[160:163], v[6:9]
	v_mfma_f32_16x16x32_bf16 v[2:5], v[212:215], v[160:163], v[2:5]
	v_mfma_f32_16x16x32_bf16 v[66:69], v[188:191], v[164:167], v[66:69]
	v_mfma_f32_16x16x32_bf16 v[70:73], v[192:195], v[164:167], v[70:73]
	v_mfma_f32_16x16x32_bf16 v[82:85], v[208:211], v[164:167], v[82:85]
	v_mfma_f32_16x16x32_bf16 v[88:91], v[212:215], v[164:167], v[88:91]
	v_mfma_f32_16x16x32_bf16 v[92:95], v[188:191], v[168:171], v[92:95]
	v_mfma_f32_16x16x32_bf16 v[96:99], v[192:195], v[168:171], v[96:99]
	v_mfma_f32_16x16x32_bf16 v[100:103], v[208:211], v[168:171], v[100:103]
	v_mfma_f32_16x16x32_bf16 v[106:109], v[212:215], v[168:171], v[106:109]
	v_mfma_f32_16x16x32_bf16 v[110:113], v[188:191], v[174:177], v[110:113]
	v_mfma_f32_16x16x32_bf16 v[114:117], v[192:195], v[174:177], v[114:117]
	v_mfma_f32_16x16x32_bf16 v[118:121], v[208:211], v[174:177], v[118:121]
	v_mfma_f32_16x16x32_bf16 v[122:125], v[212:215], v[174:177], v[122:125]
	v_mfma_f32_16x16x32_bf16 v[126:129], v[188:191], v[182:185], v[126:129]
	v_mfma_f32_16x16x32_bf16 v[136:139], v[192:195], v[182:185], v[136:139]
	v_mfma_f32_16x16x32_bf16 v[140:143], v[208:211], v[182:185], v[140:143]
	v_mfma_f32_16x16x32_bf16 v[144:147], v[212:215], v[182:185], v[144:147]
	s_add_i32 s59, s59, -1
	s_cmp_lg_u32 s59, 0
	s_cbranch_scc1 .Lg2_k
	s_waitcnt vmcnt(0)
	s_barrier
	s_add_i32 m0, s58, 0xc000
	s_nop 0
	global_load_lds_dwordx4 v74, s[56:57]
	s_add_i32 m0, s58, 0xd000
	s_nop 0
	global_load_lds_dwordx4 v75, s[56:57]
	s_add_i32 m0, s58, 0xe000
	s_nop 0
	global_load_lds_dwordx4 v76, s[56:57]
	s_add_i32 m0, s58, 0xf000
	s_nop 0
	global_load_lds_dwordx4 v77, s[56:57]
	s_add_u32 s56, s56, 0x80
	s_addc_u32 s57, s57, 0
	ds_read_b128 v[148:151], v78 offset:0
	ds_read_b128 v[152:155], v78 offset:2048
	ds_read_b128 v[156:159], v78 offset:4096
	ds_read_b128 v[160:163], v78 offset:6144
	ds_read_b128 v[188:191], v79 offset:32768
	ds_read_b128 v[192:195], v79 offset:34816
	ds_read_b128 v[208:211], v79 offset:36864
	ds_read_b128 v[212:215], v79 offset:38912
	ds_read_b128 v[164:167], v78 offset:16384
	ds_read_b128 v[168:171], v78 offset:18432
	ds_read_b128 v[174:177], v78 offset:20480
	ds_read_b128 v[182:185], v78 offset:22528
	s_waitcnt lgkmcnt(4)
	v_mfma_f32_16x16x32_bf16 v[62:65], v[188:191], v[148:151], v[62:65]
	v_mfma_f32_16x16x32_bf16 v[58:61], v[192:195], v[148:151], v[58:61]
	v_mfma_f32_16x16x32_bf16 v[54:57], v[208:211], v[148:151], v[54:57]
	v_mfma_f32_16x16x32_bf16 v[50:53], v[212:215], v[148:151], v[50:53]
	v_mfma_f32_16x16x32_bf16 v[46:49], v[188:191], v[152:155], v[46:49]
	v_mfma_f32_16x16x32_bf16 v[42:45], v[192:195], v[152:155], v[42:45]
	v_mfma_f32_16x16x32_bf16 v[38:41], v[208:211], v[152:155], v[38:41]
	v_mfma_f32_16x16x32_bf16 v[34:37], v[212:215], v[152:155], v[34:37]
	v_mfma_f32_16x16x32_bf16 v[30:33], v[188:191], v[156:159], v[30:33]
	v_mfma_f32_16x16x32_bf16 v[26:29], v[192:195], v[156:159], v[26:29]
	v_mfma_f32_16x16x32_bf16 v[22:25], v[208:211], v[156:159], v[22:25]
	v_mfma_f32_16x16x32_bf16 v[18:21], v[212:215], v[156:159], v[18:21]
	v_mfma_f32_16x16x32_bf16 v[14:17], v[188:191], v[160:163], v[14:17]
	v_mfma_f32_16x16x32_bf16 v[10:13], v[192:195], v[160:163], v[10:13]
	v_mfma_f32_16x16x32_bf16 v[6:9], v[208:211], v[160:163], v[6:9]
	v_mfma_f32_16x16x32_bf16 v[2:5], v[212:215], v[160:163], v[2:5]
	s_waitcnt lgkmcnt(0)
	v_mfma_f32_16x16x32_bf16 v[66:69], v[188:191], v[164:167], v[66:69]
	v_mfma_f32_16x16x32_bf16 v[70:73], v[192:195], v[164:167], v[70:73]
	v_mfma_f32_16x16x32_bf16 v[82:85], v[208:211], v[164:167], v[82:85]
	v_mfma_f32_16x16x32_bf16 v[88:91], v[212:215], v[164:167], v[88:91]
	v_mfma_f32_16x16x32_bf16 v[92:95], v[188:191], v[168:171], v[92:95]
	v_mfma_f32_16x16x32_bf16 v[96:99], v[192:195], v[168:171], v[96:99]
	v_mfma_f32_16x16x32_bf16 v[100:103], v[208:211], v[168:171], v[100:103]
	v_mfma_f32_16x16x32_bf16 v[106:109], v[212:215], v[168:171], v[106:109]
	v_mfma_f32_16x16x32_bf16 v[110:113], v[188:191], v[174:177], v[110:113]
	v_mfma_f32_16x16x32_bf16 v[114:117], v[192:195], v[174:177], v[114:117]
	v_mfma_f32_16x16x32_bf16 v[118:121], v[208:211], v[174:177], v[118:121]
	v_mfma_f32_16x16x32_bf16 v[122:125], v[212:215], v[174:177], v[122:125]
	v_mfma_f32_16x16x32_bf16 v[126:129], v[188:191], v[182:185], v[126:129]
	v_mfma_f32_16x16x32_bf16 v[136:139], v[192:195], v[182:185], v[136:139]
	v_mfma_f32_16x16x32_bf16 v[140:143], v[208:211], v[182:185], v[140:143]
	v_mfma_f32_16x16x32_bf16 v[144:147], v[212:215], v[182:185], v[144:147]
	ds_read_b128 v[148:151], v80 offset:0
	ds_read_b128 v[152:155], v80 offset:2048
	ds_read_b128 v[156:159], v80 offset:4096
	ds_read_b128 v[160:163], v80 offset:6144
	ds_read_b128 v[188:191], v81 offset:32768
	ds_read_b128 v[192:195], v81 offset:34816
	ds_read_b128 v[208:211], v81 offset:36864
	ds_read_b128 v[212:215], v81 offset:38912
	ds_read_b128 v[164:167], v80 offset:16384
	ds_read_b128 v[168:171], v80 offset:18432
	ds_read_b128 v[174:177], v80 offset:20480
	ds_read_b128 v[182:185], v80 offset:22528
	s_waitcnt lgkmcnt(0)
	s_barrier
	s_add_i32 m0, s58, 0x0
	s_nop 0
	global_load_lds_dwordx4 v74, s[50:51]
	s_add_i32 m0, s58, 0x1000
	s_nop 0
	global_load_lds_dwordx4 v75, s[50:51]
	s_add_i32 m0, s58, 0x2000
	s_nop 0
	global_load_lds_dwordx4 v76, s[50:51]
	s_add_i32 m0, s58, 0x3000
	s_nop 0
	global_load_lds_dwordx4 v77, s[50:51]
	s_add_i32 m0, s58, 0x4000
	s_nop 0
	global_load_lds_dwordx4 v74, s[52:53]
	s_add_i32 m0, s58, 0x5000
	s_nop 0
	global_load_lds_dwordx4 v75, s[52:53]
	s_add_i32 m0, s58, 0x6000
	s_nop 0
	global_load_lds_dwordx4 v76, s[52:53]
	s_add_i32 m0, s58, 0x7000
	s_nop 0
	global_load_lds_dwordx4 v77, s[52:53]
	s_add_u32 s50, s50, 0x80
	s_addc_u32 s51, s51, 0
	s_add_u32 s52, s52, 0x80
	s_addc_u32 s53, s53, 0
	v_mfma_f32_16x16x32_bf16 v[62:65], v[188:191], v[148:151], v[62:65]
	v_mfma_f32_16x16x32_bf16 v[58:61], v[192:195], v[148:151], v[58:61]
	v_mfma_f32_16x16x32_bf16 v[54:57], v[208:211], v[148:151], v[54:57]
	v_mfma_f32_16x16x32_bf16 v[50:53], v[212:215], v[148:151], v[50:53]
	v_mfma_f32_16x16x32_bf16 v[46:49], v[188:191], v[152:155], v[46:49]
	v_mfma_f32_16x16x32_bf16 v[42:45], v[192:195], v[152:155], v[42:45]
	v_mfma_f32_16x16x32_bf16 v[38:41], v[208:211], v[152:155], v[38:41]
	v_mfma_f32_16x16x32_bf16 v[34:37], v[212:215], v[152:155], v[34:37]
	v_mfma_f32_16x16x32_bf16 v[30:33], v[188:191], v[156:159], v[30:33]
	v_mfma_f32_16x16x32_bf16 v[26:29], v[192:195], v[156:159], v[26:29]
	v_mfma_f32_16x16x32_bf16 v[22:25], v[208:211], v[156:159], v[22:25]
	v_mfma_f32_16x16x32_bf16 v[18:21], v[212:215], v[156:159], v[18:21]
	v_mfma_f32_16x16x32_bf16 v[14:17], v[188:191], v[160:163], v[14:17]
	v_mfma_f32_16x16x32_bf16 v[10:13], v[192:195], v[160:163], v[10:13]
	v_mfma_f32_16x16x32_bf16 v[6:9], v[208:211], v[160:163], v[6:9]
	v_mfma_f32_16x16x32_bf16 v[2:5], v[212:215], v[160:163], v[2:5]
	v_mfma_f32_16x16x32_bf16 v[66:69], v[188:191], v[164:167], v[66:69]
	v_mfma_f32_16x16x32_bf16 v[70:73], v[192:195], v[164:167], v[70:73]
	v_mfma_f32_16x16x32_bf16 v[82:85], v[208:211], v[164:167], v[82:85]
	v_mfma_f32_16x16x32_bf16 v[88:91], v[212:215], v[164:167], v[88:91]
	v_mfma_f32_16x16x32_bf16 v[92:95], v[188:191], v[168:171], v[92:95]
	v_mfma_f32_16x16x32_bf16 v[96:99], v[192:195], v[168:171], v[96:99]
	v_mfma_f32_16x16x32_bf16 v[100:103], v[208:211], v[168:171], v[100:103]
	v_mfma_f32_16x16x32_bf16 v[106:109], v[212:215], v[168:171], v[106:109]
	v_mfma_f32_16x16x32_bf16 v[110:113], v[188:191], v[174:177], v[110:113]
	v_mfma_f32_16x16x32_bf16 v[114:117], v[192:195], v[174:177], v[114:117]
	v_mfma_f32_16x16x32_bf16 v[118:121], v[208:211], v[174:177], v[118:121]
	v_mfma_f32_16x16x32_bf16 v[122:125], v[212:215], v[174:177], v[122:125]
	v_mfma_f32_16x16x32_bf16 v[126:129], v[188:191], v[182:185], v[126:129]
	v_mfma_f32_16x16x32_bf16 v[136:139], v[192:195], v[182:185], v[136:139]
	v_mfma_f32_16x16x32_bf16 v[140:143], v[208:211], v[182:185], v[140:143]
	v_mfma_f32_16x16x32_bf16 v[144:147], v[212:215], v[182:185], v[144:147]
	s_waitcnt vmcnt(0)
	s_barrier
	ds_read_b128 v[148:151], v78 offset:0
	ds_read_b128 v[152:155], v78 offset:2048
	ds_read_b128 v[156:159], v78 offset:4096
	ds_read_b128 v[160:163], v78 offset:6144
	ds_read_b128 v[188:191], v79 offset:49152
	ds_read_b128 v[192:195], v79 offset:51200
	ds_read_b128 v[208:211], v79 offset:53248
	ds_read_b128 v[212:215], v79 offset:55296
	ds_read_b128 v[164:167], v78 offset:16384
	ds_read_b128 v[168:171], v78 offset:18432
	ds_read_b128 v[174:177], v78 offset:20480
	ds_read_b128 v[182:185], v78 offset:22528
	s_waitcnt lgkmcnt(4)
	v_mfma_f32_16x16x32_bf16 v[62:65], v[188:191], v[148:151], v[62:65]
	v_mfma_f32_16x16x32_bf16 v[58:61], v[192:195], v[148:151], v[58:61]
	v_mfma_f32_16x16x32_bf16 v[54:57], v[208:211], v[148:151], v[54:57]
	v_mfma_f32_16x16x32_bf16 v[50:53], v[212:215], v[148:151], v[50:53]
	v_mfma_f32_16x16x32_bf16 v[46:49], v[188:191], v[152:155], v[46:49]
	v_mfma_f32_16x16x32_bf16 v[42:45], v[192:195], v[152:155], v[42:45]
	v_mfma_f32_16x16x32_bf16 v[38:41], v[208:211], v[152:155], v[38:41]
	v_mfma_f32_16x16x32_bf16 v[34:37], v[212:215], v[152:155], v[34:37]
	v_mfma_f32_16x16x32_bf16 v[30:33], v[188:191], v[156:159], v[30:33]
	v_mfma_f32_16x16x32_bf16 v[26:29], v[192:195], v[156:159], v[26:29]
	v_mfma_f32_16x16x32_bf16 v[22:25], v[208:211], v[156:159], v[22:25]
	v_mfma_f32_16x16x32_bf16 v[18:21], v[212:215], v[156:159], v[18:21]
	v_mfma_f32_16x16x32_bf16 v[14:17], v[188:191], v[160:163], v[14:17]
	v_mfma_f32_16x16x32_bf16 v[10:13], v[192:195], v[160:163], v[10:13]
	v_mfma_f32_16x16x32_bf16 v[6:9], v[208:211], v[160:163], v[6:9]
	v_mfma_f32_16x16x32_bf16 v[2:5], v[212:215], v[160:163], v[2:5]
	s_waitcnt lgkmcnt(0)
	v_mfma_f32_16x16x32_bf16 v[66:69], v[188:191], v[164:167], v[66:69]
	v_mfma_f32_16x16x32_bf16 v[70:73], v[192:195], v[164:167], v[70:73]
	v_mfma_f32_16x16x32_bf16 v[82:85], v[208:211], v[164:167], v[82:85]
	v_mfma_f32_16x16x32_bf16 v[88:91], v[212:215], v[164:167], v[88:91]
	v_mfma_f32_16x16x32_bf16 v[92:95], v[188:191], v[168:171], v[92:95]
	v_mfma_f32_16x16x32_bf16 v[96:99], v[192:195], v[168:171], v[96:99]
	v_mfma_f32_16x16x32_bf16 v[100:103], v[208:211], v[168:171], v[100:103]
	v_mfma_f32_16x16x32_bf16 v[106:109], v[212:215], v[168:171], v[106:109]
	v_mfma_f32_16x16x32_bf16 v[110:113], v[188:191], v[174:177], v[110:113]
	v_mfma_f32_16x16x32_bf16 v[114:117], v[192:195], v[174:177], v[114:117]
	v_mfma_f32_16x16x32_bf16 v[118:121], v[208:211], v[174:177], v[118:121]
	v_mfma_f32_16x16x32_bf16 v[122:125], v[212:215], v[174:177], v[122:125]
	v_mfma_f32_16x16x32_bf16 v[126:129], v[188:191], v[182:185], v[126:129]
	v_mfma_f32_16x16x32_bf16 v[136:139], v[192:195], v[182:185], v[136:139]
	v_mfma_f32_16x16x32_bf16 v[140:143], v[208:211], v[182:185], v[140:143]
	v_mfma_f32_16x16x32_bf16 v[144:147], v[212:215], v[182:185], v[144:147]
	ds_read_b128 v[148:151], v80 offset:0
	ds_read_b128 v[152:155], v80 offset:2048
	ds_read_b128 v[156:159], v80 offset:4096
	ds_read_b128 v[160:163], v80 offset:6144
	ds_read_b128 v[188:191], v81 offset:49152
	ds_read_b128 v[192:195], v81 offset:51200
	ds_read_b128 v[208:211], v81 offset:53248
	ds_read_b128 v[212:215], v81 offset:55296
	ds_read_b128 v[164:167], v80 offset:16384
	ds_read_b128 v[168:171], v80 offset:18432
	ds_read_b128 v[174:177], v80 offset:20480
	ds_read_b128 v[182:185], v80 offset:22528
	s_waitcnt lgkmcnt(4)
	v_mfma_f32_16x16x32_bf16 v[62:65], v[188:191], v[148:151], v[62:65]
	v_mfma_f32_16x16x32_bf16 v[58:61], v[192:195], v[148:151], v[58:61]
	v_mfma_f32_16x16x32_bf16 v[54:57], v[208:211], v[148:151], v[54:57]
	v_mfma_f32_16x16x32_bf16 v[50:53], v[212:215], v[148:151], v[50:53]
	v_mfma_f32_16x16x32_bf16 v[46:49], v[188:191], v[152:155], v[46:49]
	v_mfma_f32_16x16x32_bf16 v[42:45], v[192:195], v[152:155], v[42:45]
	v_mfma_f32_16x16x32_bf16 v[38:41], v[208:211], v[152:155], v[38:41]
	v_mfma_f32_16x16x32_bf16 v[34:37], v[212:215], v[152:155], v[34:37]
	v_mfma_f32_16x16x32_bf16 v[30:33], v[188:191], v[156:159], v[30:33]
	v_mfma_f32_16x16x32_bf16 v[26:29], v[192:195], v[156:159], v[26:29]
	v_mfma_f32_16x16x32_bf16 v[22:25], v[208:211], v[156:159], v[22:25]
	v_mfma_f32_16x16x32_bf16 v[18:21], v[212:215], v[156:159], v[18:21]
	v_mfma_f32_16x16x32_bf16 v[14:17], v[188:191], v[160:163], v[14:17]
	v_mfma_f32_16x16x32_bf16 v[10:13], v[192:195], v[160:163], v[10:13]
	v_mfma_f32_16x16x32_bf16 v[6:9], v[208:211], v[160:163], v[6:9]
	v_mfma_f32_16x16x32_bf16 v[2:5], v[212:215], v[160:163], v[2:5]
	s_waitcnt lgkmcnt(0)
	v_mfma_f32_16x16x32_bf16 v[66:69], v[188:191], v[164:167], v[66:69]
	v_mfma_f32_16x16x32_bf16 v[70:73], v[192:195], v[164:167], v[70:73]
	v_mfma_f32_16x16x32_bf16 v[82:85], v[208:211], v[164:167], v[82:85]
	v_mfma_f32_16x16x32_bf16 v[88:91], v[212:215], v[164:167], v[88:91]
	v_mfma_f32_16x16x32_bf16 v[92:95], v[188:191], v[168:171], v[92:95]
	v_mfma_f32_16x16x32_bf16 v[96:99], v[192:195], v[168:171], v[96:99]
	v_mfma_f32_16x16x32_bf16 v[100:103], v[208:211], v[168:171], v[100:103]
	v_mfma_f32_16x16x32_bf16 v[106:109], v[212:215], v[168:171], v[106:109]
	v_mfma_f32_16x16x32_bf16 v[110:113], v[188:191], v[174:177], v[110:113]
	v_mfma_f32_16x16x32_bf16 v[114:117], v[192:195], v[174:177], v[114:117]
	v_mfma_f32_16x16x32_bf16 v[118:121], v[208:211], v[174:177], v[118:121]
	v_mfma_f32_16x16x32_bf16 v[122:125], v[212:215], v[174:177], v[122:125]
	v_mfma_f32_16x16x32_bf16 v[126:129], v[188:191], v[182:185], v[126:129]
	v_mfma_f32_16x16x32_bf16 v[136:139], v[192:195], v[182:185], v[136:139]
	v_mfma_f32_16x16x32_bf16 v[140:143], v[208:211], v[182:185], v[140:143]
	v_mfma_f32_16x16x32_bf16 v[144:147], v[212:215], v[182:185], v[144:147]
	s_nop 7
	s_nop 7
	s_nop 7
	v_mov_b32_e32 v148, v66
	v_mov_b32_e32 v149, v67
	v_mov_b32_e32 v150, v68
	v_mov_b32_e32 v151, v69
	v_mov_b32_e32 v152, v70
	v_mov_b32_e32 v153, v71
	v_mov_b32_e32 v154, v72
	v_mov_b32_e32 v155, v73
	v_mov_b32_e32 v156, v82
	v_mov_b32_e32 v157, v83
	v_mov_b32_e32 v158, v84
	v_mov_b32_e32 v159, v85
	v_mov_b32_e32 v160, v88
	v_mov_b32_e32 v161, v89
	v_mov_b32_e32 v162, v90
	v_mov_b32_e32 v163, v91
	v_mov_b32_e32 v164, v92
	v_mov_b32_e32 v165, v93
	v_mov_b32_e32 v166, v94
	v_mov_b32_e32 v167, v95
	v_mov_b32_e32 v168, v96
	v_mov_b32_e32 v169, v97
	v_mov_b32_e32 v170, v98
	v_mov_b32_e32 v171, v99
	v_mov_b32_e32 v174, v100
	v_mov_b32_e32 v175, v101
	v_mov_b32_e32 v176, v102
	v_mov_b32_e32 v177, v103
	v_mov_b32_e32 v182, v106
	v_mov_b32_e32 v183, v107
	v_mov_b32_e32 v184, v108
	v_mov_b32_e32 v185, v109
	v_mov_b32_e32 v188, v110
	v_mov_b32_e32 v189, v111
	v_mov_b32_e32 v190, v112
	v_mov_b32_e32 v191, v113
	v_mov_b32_e32 v192, v114
	v_mov_b32_e32 v193, v115
	v_mov_b32_e32 v194, v116
	v_mov_b32_e32 v195, v117
	v_mov_b32_e32 v208, v118
	v_mov_b32_e32 v209, v119
	v_mov_b32_e32 v210, v120
	v_mov_b32_e32 v211, v121
	v_mov_b32_e32 v212, v122
	v_mov_b32_e32 v213, v123
	v_mov_b32_e32 v214, v124
	v_mov_b32_e32 v215, v125
	v_mov_b32_e32 v216, v126
	v_mov_b32_e32 v217, v127
	v_mov_b32_e32 v218, v128
	v_mov_b32_e32 v219, v129
	v_mov_b32_e32 v220, v136
	v_mov_b32_e32 v221, v137
	v_mov_b32_e32 v222, v138
	v_mov_b32_e32 v223, v139
	v_mov_b32_e32 v242, v140
	v_mov_b32_e32 v243, v141
	v_mov_b32_e32 v244, v142
	v_mov_b32_e32 v245, v143
	v_mov_b32_e32 v199, v144
	v_mov_b32_e32 v206, v145
	v_mov_b32_e32 v207, v146
	v_mov_b32_e32 v226, v147
	s_add_i32 s48, s48, 1
	s_mov_b32 s65, 0
	v_readlane_b32 s2, v249, 0
	s_nop 0
	s_and_b32 s3, s2, 7
	s_lshr_b32 s2, s2, 3
	s_cmp_lt_u32 s2, 40
	s_cselect_b32 s38, 7, 6
	s_cmp_lt_u32 s48, s38
	s_cbranch_scc0 .Lg2_c1_extra
	s_lshl_b32 s20, s48, 6
	s_add_i32 s20, s20, s2
	s_cmp_ge_u32 s20, 0xd4
	s_cselect_b32 s21, 1, 0
	s_mul_i32 s60, s21, 0xd4
	s_sub_i32 s20, s20, s60
	s_lshr_b32 s61, s20, 2
	s_and_b32 s20, s20, 3
	s_lshl_b32 s21, s21, 3
	s_add_i32 s20, s20, s21
	s_lshl_b32 s20, s20, 3
	s_add_i32 s60, s20, s3
	s_add_i32 s64, s60, 32
	s_branch .Lg2_c1_have

.Lr2u_k:
	s_waitcnt vmcnt(0)
	s_barrier
	s_add_i32 m0, s36, 0xc000
	s_nop 0
	global_load_lds_dwordx4 v136, s[34:35]
	s_add_i32 m0, s36, 0xd000
	s_nop 0
	global_load_lds_dwordx4 v137, s[34:35]
	s_add_i32 m0, s36, 0xe000
	s_nop 0
	global_load_lds_dwordx4 v138, s[34:35]
	s_add_i32 m0, s36, 0xf000
	s_nop 0
	global_load_lds_dwordx4 v139, s[34:35]
	s_add_u32 s34, s34, 0x80
	s_addc_u32 s35, s35, 0
	ds_read_b128 v[148:151], v140 offset:0
	ds_read_b128 v[152:155], v140 offset:2048
	ds_read_b128 v[156:159], v140 offset:4096
	ds_read_b128 v[160:163], v140 offset:6144
	ds_read_b128 v[164:167], v140 offset:16384
	ds_read_b128 v[168:171], v140 offset:18432
	ds_read_b128 v[174:177], v140 offset:20480
	ds_read_b128 v[182:185], v140 offset:22528
	ds_read_b128 v[188:191], v142 offset:32768
	ds_read_b128 v[192:195], v142 offset:34816
	ds_read_b128 v[208:211], v142 offset:36864
	ds_read_b128 v[212:215], v142 offset:38912
	s_waitcnt lgkmcnt(0)
	v_mfma_f32_16x16x32_bf16 v[62:65], v[188:191], v[148:151], v[62:65]
	v_mfma_f32_16x16x32_bf16 v[58:61], v[192:195], v[148:151], v[58:61]
	v_mfma_f32_16x16x32_bf16 v[54:57], v[208:211], v[148:151], v[54:57]
	v_mfma_f32_16x16x32_bf16 v[50:53], v[212:215], v[148:151], v[50:53]
	v_mfma_f32_16x16x32_bf16 v[46:49], v[188:191], v[152:155], v[46:49]
	v_mfma_f32_16x16x32_bf16 v[42:45], v[192:195], v[152:155], v[42:45]
	v_mfma_f32_16x16x32_bf16 v[38:41], v[208:211], v[152:155], v[38:41]
	v_mfma_f32_16x16x32_bf16 v[34:37], v[212:215], v[152:155], v[34:37]
	v_mfma_f32_16x16x32_bf16 v[30:33], v[188:191], v[156:159], v[30:33]
	v_mfma_f32_16x16x32_bf16 v[26:29], v[192:195], v[156:159], v[26:29]
	v_mfma_f32_16x16x32_bf16 v[22:25], v[208:211], v[156:159], v[22:25]
	v_mfma_f32_16x16x32_bf16 v[18:21], v[212:215], v[156:159], v[18:21]
	v_mfma_f32_16x16x32_bf16 v[14:17], v[188:191], v[160:163], v[14:17]
	v_mfma_f32_16x16x32_bf16 v[10:13], v[192:195], v[160:163], v[10:13]
	v_mfma_f32_16x16x32_bf16 v[6:9], v[208:211], v[160:163], v[6:9]
	v_mfma_f32_16x16x32_bf16 v[2:5], v[212:215], v[160:163], v[2:5]
	v_mfma_f32_16x16x32_bf16 v[66:69], v[188:191], v[164:167], v[66:69]
	v_mfma_f32_16x16x32_bf16 v[70:73], v[192:195], v[164:167], v[70:73]
	v_mfma_f32_16x16x32_bf16 v[74:77], v[208:211], v[164:167], v[74:77]
	v_mfma_f32_16x16x32_bf16 v[78:81], v[212:215], v[164:167], v[78:81]
	v_mfma_f32_16x16x32_bf16 v[82:85], v[188:191], v[168:171], v[82:85]
	v_mfma_f32_16x16x32_bf16 v[86:89], v[192:195], v[168:171], v[86:89]
	v_mfma_f32_16x16x32_bf16 v[90:93], v[208:211], v[168:171], v[90:93]
	v_mfma_f32_16x16x32_bf16 v[94:97], v[212:215], v[168:171], v[94:97]
	v_mfma_f32_16x16x32_bf16 v[98:101], v[188:191], v[174:177], v[98:101]
	v_mfma_f32_16x16x32_bf16 v[102:105], v[192:195], v[174:177], v[102:105]
	v_mfma_f32_16x16x32_bf16 v[106:109], v[208:211], v[174:177], v[106:109]
	v_mfma_f32_16x16x32_bf16 v[110:113], v[212:215], v[174:177], v[110:113]
	v_mfma_f32_16x16x32_bf16 v[114:117], v[188:191], v[182:185], v[114:117]
	v_mfma_f32_16x16x32_bf16 v[118:121], v[192:195], v[182:185], v[118:121]
	v_mfma_f32_16x16x32_bf16 v[122:125], v[208:211], v[182:185], v[122:125]
	v_mfma_f32_16x16x32_bf16 v[126:129], v[212:215], v[182:185], v[126:129]
	ds_read_b128 v[148:151], v141 offset:0
	ds_read_b128 v[152:155], v141 offset:2048
	ds_read_b128 v[156:159], v141 offset:4096
	ds_read_b128 v[160:163], v141 offset:6144
	ds_read_b128 v[164:167], v141 offset:16384
	ds_read_b128 v[168:171], v141 offset:18432
	ds_read_b128 v[174:177], v141 offset:20480
	ds_read_b128 v[182:185], v141 offset:22528
	ds_read_b128 v[188:191], v143 offset:32768
	ds_read_b128 v[192:195], v143 offset:34816
	ds_read_b128 v[208:211], v143 offset:36864
	ds_read_b128 v[212:215], v143 offset:38912
	s_waitcnt lgkmcnt(0)
	s_barrier
	s_add_i32 m0, s36, 0x0
	s_nop 0
	global_load_lds_dwordx4 v136, s[30:31]
	s_add_i32 m0, s36, 0x1000
	s_nop 0
	global_load_lds_dwordx4 v137, s[30:31]
	s_add_i32 m0, s36, 0x2000
	s_nop 0
	global_load_lds_dwordx4 v138, s[30:31]
	s_add_i32 m0, s36, 0x3000
	s_nop 0
	global_load_lds_dwordx4 v139, s[30:31]
	s_add_i32 m0, s36, 0x4000
	s_nop 0
	global_load_lds_dwordx4 v136, s[44:45]
	s_add_i32 m0, s36, 0x5000
	s_nop 0
	global_load_lds_dwordx4 v137, s[44:45]
	s_add_i32 m0, s36, 0x6000
	s_nop 0
	global_load_lds_dwordx4 v138, s[44:45]
	s_add_i32 m0, s36, 0x7000
	s_nop 0
	global_load_lds_dwordx4 v139, s[44:45]
	s_add_u32 s30, s30, 0x80
	s_addc_u32 s31, s31, 0
	s_add_u32 s44, s44, 0x80
	s_addc_u32 s45, s45, 0
	v_mfma_f32_16x16x32_bf16 v[62:65], v[188:191], v[148:151], v[62:65]
	v_mfma_f32_16x16x32_bf16 v[58:61], v[192:195], v[148:151], v[58:61]
	v_mfma_f32_16x16x32_bf16 v[54:57], v[208:211], v[148:151], v[54:57]
	v_mfma_f32_16x16x32_bf16 v[50:53], v[212:215], v[148:151], v[50:53]
	v_mfma_f32_16x16x32_bf16 v[46:49], v[188:191], v[152:155], v[46:49]
	v_mfma_f32_16x16x32_bf16 v[42:45], v[192:195], v[152:155], v[42:45]
	v_mfma_f32_16x16x32_bf16 v[38:41], v[208:211], v[152:155], v[38:41]
	v_mfma_f32_16x16x32_bf16 v[34:37], v[212:215], v[152:155], v[34:37]
	v_mfma_f32_16x16x32_bf16 v[30:33], v[188:191], v[156:159], v[30:33]
	v_mfma_f32_16x16x32_bf16 v[26:29], v[192:195], v[156:159], v[26:29]
	v_mfma_f32_16x16x32_bf16 v[22:25], v[208:211], v[156:159], v[22:25]
	v_mfma_f32_16x16x32_bf16 v[18:21], v[212:215], v[156:159], v[18:21]
	v_mfma_f32_16x16x32_bf16 v[14:17], v[188:191], v[160:163], v[14:17]
	v_mfma_f32_16x16x32_bf16 v[10:13], v[192:195], v[160:163], v[10:13]
	v_mfma_f32_16x16x32_bf16 v[6:9], v[208:211], v[160:163], v[6:9]
	v_mfma_f32_16x16x32_bf16 v[2:5], v[212:215], v[160:163], v[2:5]
	v_mfma_f32_16x16x32_bf16 v[66:69], v[188:191], v[164:167], v[66:69]
	v_mfma_f32_16x16x32_bf16 v[70:73], v[192:195], v[164:167], v[70:73]
	v_mfma_f32_16x16x32_bf16 v[74:77], v[208:211], v[164:167], v[74:77]
	v_mfma_f32_16x16x32_bf16 v[78:81], v[212:215], v[164:167], v[78:81]
	v_mfma_f32_16x16x32_bf16 v[82:85], v[188:191], v[168:171], v[82:85]
	v_mfma_f32_16x16x32_bf16 v[86:89], v[192:195], v[168:171], v[86:89]
	v_mfma_f32_16x16x32_bf16 v[90:93], v[208:211], v[168:171], v[90:93]
	v_mfma_f32_16x16x32_bf16 v[94:97], v[212:215], v[168:171], v[94:97]
	v_mfma_f32_16x16x32_bf16 v[98:101], v[188:191], v[174:177], v[98:101]
	v_mfma_f32_16x16x32_bf16 v[102:105], v[192:195], v[174:177], v[102:105]
	v_mfma_f32_16x16x32_bf16 v[106:109], v[208:211], v[174:177], v[106:109]
	v_mfma_f32_16x16x32_bf16 v[110:113], v[212:215], v[174:177], v[110:113]
	v_mfma_f32_16x16x32_bf16 v[114:117], v[188:191], v[182:185], v[114:117]
	v_mfma_f32_16x16x32_bf16 v[118:121], v[192:195], v[182:185], v[118:121]
	v_mfma_f32_16x16x32_bf16 v[122:125], v[208:211], v[182:185], v[122:125]
	v_mfma_f32_16x16x32_bf16 v[126:129], v[212:215], v[182:185], v[126:129]
	s_waitcnt vmcnt(0)
	s_barrier
	s_add_i32 m0, s36, 0x8000
	s_nop 0
	global_load_lds_dwordx4 v136, s[34:35]
	s_add_i32 m0, s36, 0x9000
	s_nop 0
	global_load_lds_dwordx4 v137, s[34:35]
	s_add_i32 m0, s36, 0xa000
	s_nop 0
	global_load_lds_dwordx4 v138, s[34:35]
	s_add_i32 m0, s36, 0xb000
	s_nop 0
	global_load_lds_dwordx4 v139, s[34:35]
	s_add_u32 s34, s34, 0x80
	s_addc_u32 s35, s35, 0
	ds_read_b128 v[148:151], v140 offset:0
	ds_read_b128 v[152:155], v140 offset:2048
	ds_read_b128 v[156:159], v140 offset:4096
	ds_read_b128 v[160:163], v140 offset:6144
	ds_read_b128 v[164:167], v140 offset:16384
	ds_read_b128 v[168:171], v140 offset:18432
	ds_read_b128 v[174:177], v140 offset:20480
	ds_read_b128 v[182:185], v140 offset:22528
	ds_read_b128 v[188:191], v142 offset:49152
	ds_read_b128 v[192:195], v142 offset:51200
	ds_read_b128 v[208:211], v142 offset:53248
	ds_read_b128 v[212:215], v142 offset:55296
	s_waitcnt lgkmcnt(0)
	v_mfma_f32_16x16x32_bf16 v[62:65], v[188:191], v[148:151], v[62:65]
	v_mfma_f32_16x16x32_bf16 v[58:61], v[192:195], v[148:151], v[58:61]
	v_mfma_f32_16x16x32_bf16 v[54:57], v[208:211], v[148:151], v[54:57]
	v_mfma_f32_16x16x32_bf16 v[50:53], v[212:215], v[148:151], v[50:53]
	v_mfma_f32_16x16x32_bf16 v[46:49], v[188:191], v[152:155], v[46:49]
	v_mfma_f32_16x16x32_bf16 v[42:45], v[192:195], v[152:155], v[42:45]
	v_mfma_f32_16x16x32_bf16 v[38:41], v[208:211], v[152:155], v[38:41]
	v_mfma_f32_16x16x32_bf16 v[34:37], v[212:215], v[152:155], v[34:37]
	v_mfma_f32_16x16x32_bf16 v[30:33], v[188:191], v[156:159], v[30:33]
	v_mfma_f32_16x16x32_bf16 v[26:29], v[192:195], v[156:159], v[26:29]
	v_mfma_f32_16x16x32_bf16 v[22:25], v[208:211], v[156:159], v[22:25]
	v_mfma_f32_16x16x32_bf16 v[18:21], v[212:215], v[156:159], v[18:21]
	v_mfma_f32_16x16x32_bf16 v[14:17], v[188:191], v[160:163], v[14:17]
	v_mfma_f32_16x16x32_bf16 v[10:13], v[192:195], v[160:163], v[10:13]
	v_mfma_f32_16x16x32_bf16 v[6:9], v[208:211], v[160:163], v[6:9]
	v_mfma_f32_16x16x32_bf16 v[2:5], v[212:215], v[160:163], v[2:5]
	v_mfma_f32_16x16x32_bf16 v[66:69], v[188:191], v[164:167], v[66:69]
	v_mfma_f32_16x16x32_bf16 v[70:73], v[192:195], v[164:167], v[70:73]
	v_mfma_f32_16x16x32_bf16 v[74:77], v[208:211], v[164:167], v[74:77]
	v_mfma_f32_16x16x32_bf16 v[78:81], v[212:215], v[164:167], v[78:81]
	v_mfma_f32_16x16x32_bf16 v[82:85], v[188:191], v[168:171], v[82:85]
	v_mfma_f32_16x16x32_bf16 v[86:89], v[192:195], v[168:171], v[86:89]
	v_mfma_f32_16x16x32_bf16 v[90:93], v[208:211], v[168:171], v[90:93]
	v_mfma_f32_16x16x32_bf16 v[94:97], v[212:215], v[168:171], v[94:97]
	v_mfma_f32_16x16x32_bf16 v[98:101], v[188:191], v[174:177], v[98:101]
	v_mfma_f32_16x16x32_bf16 v[102:105], v[192:195], v[174:177], v[102:105]
	v_mfma_f32_16x16x32_bf16 v[106:109], v[208:211], v[174:177], v[106:109]
	v_mfma_f32_16x16x32_bf16 v[110:113], v[212:215], v[174:177], v[110:113]
	v_mfma_f32_16x16x32_bf16 v[114:117], v[188:191], v[182:185], v[114:117]
	v_mfma_f32_16x16x32_bf16 v[118:121], v[192:195], v[182:185], v[118:121]
	v_mfma_f32_16x16x32_bf16 v[122:125], v[208:211], v[182:185], v[122:125]
	v_mfma_f32_16x16x32_bf16 v[126:129], v[212:215], v[182:185], v[126:129]
	ds_read_b128 v[148:151], v141 offset:0
	ds_read_b128 v[152:155], v141 offset:2048
	ds_read_b128 v[156:159], v141 offset:4096
	ds_read_b128 v[160:163], v141 offset:6144
	ds_read_b128 v[164:167], v141 offset:16384
	ds_read_b128 v[168:171], v141 offset:18432
	ds_read_b128 v[174:177], v141 offset:20480
	ds_read_b128 v[182:185], v141 offset:22528
	ds_read_b128 v[188:191], v143 offset:49152
	ds_read_b128 v[192:195], v143 offset:51200
	ds_read_b128 v[208:211], v143 offset:53248
	ds_read_b128 v[212:215], v143 offset:55296
	s_waitcnt lgkmcnt(0)
	s_barrier
	s_add_i32 m0, s36, 0x0
	s_nop 0
	global_load_lds_dwordx4 v136, s[30:31]
	s_add_i32 m0, s36, 0x1000
	s_nop 0
	global_load_lds_dwordx4 v137, s[30:31]
	s_add_i32 m0, s36, 0x2000
	s_nop 0
	global_load_lds_dwordx4 v138, s[30:31]
	s_add_i32 m0, s36, 0x3000
	s_nop 0
	global_load_lds_dwordx4 v139, s[30:31]
	s_add_i32 m0, s36, 0x4000
	s_nop 0
	global_load_lds_dwordx4 v136, s[44:45]
	s_add_i32 m0, s36, 0x5000
	s_nop 0
	global_load_lds_dwordx4 v137, s[44:45]
	s_add_i32 m0, s36, 0x6000
	s_nop 0
	global_load_lds_dwordx4 v138, s[44:45]
	s_add_i32 m0, s36, 0x7000
	s_nop 0
	global_load_lds_dwordx4 v139, s[44:45]
	s_add_u32 s30, s30, 0x80
	s_addc_u32 s31, s31, 0
	s_add_u32 s44, s44, 0x80
	s_addc_u32 s45, s45, 0
	v_mfma_f32_16x16x32_bf16 v[62:65], v[188:191], v[148:151], v[62:65]
	v_mfma_f32_16x16x32_bf16 v[58:61], v[192:195], v[148:151], v[58:61]
	v_mfma_f32_16x16x32_bf16 v[54:57], v[208:211], v[148:151], v[54:57]
	v_mfma_f32_16x16x32_bf16 v[50:53], v[212:215], v[148:151], v[50:53]
	v_mfma_f32_16x16x32_bf16 v[46:49], v[188:191], v[152:155], v[46:49]
	v_mfma_f32_16x16x32_bf16 v[42:45], v[192:195], v[152:155], v[42:45]
	v_mfma_f32_16x16x32_bf16 v[38:41], v[208:211], v[152:155], v[38:41]
	v_mfma_f32_16x16x32_bf16 v[34:37], v[212:215], v[152:155], v[34:37]
	v_mfma_f32_16x16x32_bf16 v[30:33], v[188:191], v[156:159], v[30:33]
	v_mfma_f32_16x16x32_bf16 v[26:29], v[192:195], v[156:159], v[26:29]
	v_mfma_f32_16x16x32_bf16 v[22:25], v[208:211], v[156:159], v[22:25]
	v_mfma_f32_16x16x32_bf16 v[18:21], v[212:215], v[156:159], v[18:21]
	v_mfma_f32_16x16x32_bf16 v[14:17], v[188:191], v[160:163], v[14:17]
	v_mfma_f32_16x16x32_bf16 v[10:13], v[192:195], v[160:163], v[10:13]
	v_mfma_f32_16x16x32_bf16 v[6:9], v[208:211], v[160:163], v[6:9]
	v_mfma_f32_16x16x32_bf16 v[2:5], v[212:215], v[160:163], v[2:5]
	v_mfma_f32_16x16x32_bf16 v[66:69], v[188:191], v[164:167], v[66:69]
	v_mfma_f32_16x16x32_bf16 v[70:73], v[192:195], v[164:167], v[70:73]
	v_mfma_f32_16x16x32_bf16 v[74:77], v[208:211], v[164:167], v[74:77]
	v_mfma_f32_16x16x32_bf16 v[78:81], v[212:215], v[164:167], v[78:81]
	v_mfma_f32_16x16x32_bf16 v[82:85], v[188:191], v[168:171], v[82:85]
	v_mfma_f32_16x16x32_bf16 v[86:89], v[192:195], v[168:171], v[86:89]
	v_mfma_f32_16x16x32_bf16 v[90:93], v[208:211], v[168:171], v[90:93]
	v_mfma_f32_16x16x32_bf16 v[94:97], v[212:215], v[168:171], v[94:97]
	v_mfma_f32_16x16x32_bf16 v[98:101], v[188:191], v[174:177], v[98:101]
	v_mfma_f32_16x16x32_bf16 v[102:105], v[192:195], v[174:177], v[102:105]
	v_mfma_f32_16x16x32_bf16 v[106:109], v[208:211], v[174:177], v[106:109]
	v_mfma_f32_16x16x32_bf16 v[110:113], v[212:215], v[174:177], v[110:113]
	v_mfma_f32_16x16x32_bf16 v[114:117], v[188:191], v[182:185], v[114:117]
	v_mfma_f32_16x16x32_bf16 v[118:121], v[192:195], v[182:185], v[118:121]
	v_mfma_f32_16x16x32_bf16 v[122:125], v[208:211], v[182:185], v[122:125]
	v_mfma_f32_16x16x32_bf16 v[126:129], v[212:215], v[182:185], v[126:129]
	s_add_i32 s37, s37, -1
	s_cmp_lg_u32 s37, 0
	s_cbranch_scc1 .Lr2u_k
	s_waitcnt vmcnt(0)
	s_barrier
	s_add_i32 m0, s36, 0xc000
	s_nop 0
	global_load_lds_dwordx4 v136, s[34:35]
	s_add_i32 m0, s36, 0xd000
	s_nop 0
	global_load_lds_dwordx4 v137, s[34:35]
	s_add_i32 m0, s36, 0xe000
	s_nop 0
	global_load_lds_dwordx4 v138, s[34:35]
	s_add_i32 m0, s36, 0xf000
	s_nop 0
	global_load_lds_dwordx4 v139, s[34:35]
	s_add_u32 s34, s34, 0x80
	s_addc_u32 s35, s35, 0
	ds_read_b128 v[148:151], v140 offset:0
	ds_read_b128 v[152:155], v140 offset:2048
	ds_read_b128 v[156:159], v140 offset:4096
	ds_read_b128 v[160:163], v140 offset:6144
	ds_read_b128 v[164:167], v140 offset:16384
	ds_read_b128 v[168:171], v140 offset:18432
	ds_read_b128 v[174:177], v140 offset:20480
	ds_read_b128 v[182:185], v140 offset:22528
	ds_read_b128 v[188:191], v142 offset:32768
	ds_read_b128 v[192:195], v142 offset:34816
	ds_read_b128 v[208:211], v142 offset:36864
	ds_read_b128 v[212:215], v142 offset:38912
	s_waitcnt lgkmcnt(0)
	v_mfma_f32_16x16x32_bf16 v[62:65], v[188:191], v[148:151], v[62:65]
	v_mfma_f32_16x16x32_bf16 v[58:61], v[192:195], v[148:151], v[58:61]
	v_mfma_f32_16x16x32_bf16 v[54:57], v[208:211], v[148:151], v[54:57]
	v_mfma_f32_16x16x32_bf16 v[50:53], v[212:215], v[148:151], v[50:53]
	v_mfma_f32_16x16x32_bf16 v[46:49], v[188:191], v[152:155], v[46:49]
	v_mfma_f32_16x16x32_bf16 v[42:45], v[192:195], v[152:155], v[42:45]
	v_mfma_f32_16x16x32_bf16 v[38:41], v[208:211], v[152:155], v[38:41]
	v_mfma_f32_16x16x32_bf16 v[34:37], v[212:215], v[152:155], v[34:37]
	v_mfma_f32_16x16x32_bf16 v[30:33], v[188:191], v[156:159], v[30:33]
	v_mfma_f32_16x16x32_bf16 v[26:29], v[192:195], v[156:159], v[26:29]
	v_mfma_f32_16x16x32_bf16 v[22:25], v[208:211], v[156:159], v[22:25]
	v_mfma_f32_16x16x32_bf16 v[18:21], v[212:215], v[156:159], v[18:21]
	v_mfma_f32_16x16x32_bf16 v[14:17], v[188:191], v[160:163], v[14:17]
	v_mfma_f32_16x16x32_bf16 v[10:13], v[192:195], v[160:163], v[10:13]
	v_mfma_f32_16x16x32_bf16 v[6:9], v[208:211], v[160:163], v[6:9]
	v_mfma_f32_16x16x32_bf16 v[2:5], v[212:215], v[160:163], v[2:5]
	v_mfma_f32_16x16x32_bf16 v[66:69], v[188:191], v[164:167], v[66:69]
	v_mfma_f32_16x16x32_bf16 v[70:73], v[192:195], v[164:167], v[70:73]
	v_mfma_f32_16x16x32_bf16 v[74:77], v[208:211], v[164:167], v[74:77]
	v_mfma_f32_16x16x32_bf16 v[78:81], v[212:215], v[164:167], v[78:81]
	v_mfma_f32_16x16x32_bf16 v[82:85], v[188:191], v[168:171], v[82:85]
	v_mfma_f32_16x16x32_bf16 v[86:89], v[192:195], v[168:171], v[86:89]
	v_mfma_f32_16x16x32_bf16 v[90:93], v[208:211], v[168:171], v[90:93]
	v_mfma_f32_16x16x32_bf16 v[94:97], v[212:215], v[168:171], v[94:97]
	v_mfma_f32_16x16x32_bf16 v[98:101], v[188:191], v[174:177], v[98:101]
	v_mfma_f32_16x16x32_bf16 v[102:105], v[192:195], v[174:177], v[102:105]
	v_mfma_f32_16x16x32_bf16 v[106:109], v[208:211], v[174:177], v[106:109]
	v_mfma_f32_16x16x32_bf16 v[110:113], v[212:215], v[174:177], v[110:113]
	v_mfma_f32_16x16x32_bf16 v[114:117], v[188:191], v[182:185], v[114:117]
	v_mfma_f32_16x16x32_bf16 v[118:121], v[192:195], v[182:185], v[118:121]
	v_mfma_f32_16x16x32_bf16 v[122:125], v[208:211], v[182:185], v[122:125]
	v_mfma_f32_16x16x32_bf16 v[126:129], v[212:215], v[182:185], v[126:129]
	ds_read_b128 v[148:151], v141 offset:0
	ds_read_b128 v[152:155], v141 offset:2048
	ds_read_b128 v[156:159], v141 offset:4096
	ds_read_b128 v[160:163], v141 offset:6144
	ds_read_b128 v[164:167], v141 offset:16384
	ds_read_b128 v[168:171], v141 offset:18432
	ds_read_b128 v[174:177], v141 offset:20480
	ds_read_b128 v[182:185], v141 offset:22528
	ds_read_b128 v[188:191], v143 offset:32768
	ds_read_b128 v[192:195], v143 offset:34816
	ds_read_b128 v[208:211], v143 offset:36864
	ds_read_b128 v[212:215], v143 offset:38912
	s_waitcnt lgkmcnt(0)
	s_barrier
	s_add_i32 m0, s36, 0x0
	s_nop 0
	global_load_lds_dwordx4 v136, s[30:31]
	s_add_i32 m0, s36, 0x1000
	s_nop 0
	global_load_lds_dwordx4 v137, s[30:31]
	s_add_i32 m0, s36, 0x2000
	s_nop 0
	global_load_lds_dwordx4 v138, s[30:31]
	s_add_i32 m0, s36, 0x3000
	s_nop 0
	global_load_lds_dwordx4 v139, s[30:31]
	s_add_i32 m0, s36, 0x4000
	s_nop 0
	global_load_lds_dwordx4 v136, s[44:45]
	s_add_i32 m0, s36, 0x5000
	s_nop 0
	global_load_lds_dwordx4 v137, s[44:45]
	s_add_i32 m0, s36, 0x6000
	s_nop 0
	global_load_lds_dwordx4 v138, s[44:45]
	s_add_i32 m0, s36, 0x7000
	s_nop 0
	global_load_lds_dwordx4 v139, s[44:45]
	s_add_u32 s30, s30, 0x80
	s_addc_u32 s31, s31, 0
	s_add_u32 s44, s44, 0x80
	s_addc_u32 s45, s45, 0
	v_mfma_f32_16x16x32_bf16 v[62:65], v[188:191], v[148:151], v[62:65]
	v_mfma_f32_16x16x32_bf16 v[58:61], v[192:195], v[148:151], v[58:61]
	v_mfma_f32_16x16x32_bf16 v[54:57], v[208:211], v[148:151], v[54:57]
	v_mfma_f32_16x16x32_bf16 v[50:53], v[212:215], v[148:151], v[50:53]
	v_mfma_f32_16x16x32_bf16 v[46:49], v[188:191], v[152:155], v[46:49]
	v_mfma_f32_16x16x32_bf16 v[42:45], v[192:195], v[152:155], v[42:45]
	v_mfma_f32_16x16x32_bf16 v[38:41], v[208:211], v[152:155], v[38:41]
	v_mfma_f32_16x16x32_bf16 v[34:37], v[212:215], v[152:155], v[34:37]
	v_mfma_f32_16x16x32_bf16 v[30:33], v[188:191], v[156:159], v[30:33]
	v_mfma_f32_16x16x32_bf16 v[26:29], v[192:195], v[156:159], v[26:29]
	v_mfma_f32_16x16x32_bf16 v[22:25], v[208:211], v[156:159], v[22:25]
	v_mfma_f32_16x16x32_bf16 v[18:21], v[212:215], v[156:159], v[18:21]
	v_mfma_f32_16x16x32_bf16 v[14:17], v[188:191], v[160:163], v[14:17]
	v_mfma_f32_16x16x32_bf16 v[10:13], v[192:195], v[160:163], v[10:13]
	v_mfma_f32_16x16x32_bf16 v[6:9], v[208:211], v[160:163], v[6:9]
	v_mfma_f32_16x16x32_bf16 v[2:5], v[212:215], v[160:163], v[2:5]
	v_mfma_f32_16x16x32_bf16 v[66:69], v[188:191], v[164:167], v[66:69]
	v_mfma_f32_16x16x32_bf16 v[70:73], v[192:195], v[164:167], v[70:73]
	v_mfma_f32_16x16x32_bf16 v[74:77], v[208:211], v[164:167], v[74:77]
	v_mfma_f32_16x16x32_bf16 v[78:81], v[212:215], v[164:167], v[78:81]
	v_mfma_f32_16x16x32_bf16 v[82:85], v[188:191], v[168:171], v[82:85]
	v_mfma_f32_16x16x32_bf16 v[86:89], v[192:195], v[168:171], v[86:89]
	v_mfma_f32_16x16x32_bf16 v[90:93], v[208:211], v[168:171], v[90:93]
	v_mfma_f32_16x16x32_bf16 v[94:97], v[212:215], v[168:171], v[94:97]
	v_mfma_f32_16x16x32_bf16 v[98:101], v[188:191], v[174:177], v[98:101]
	v_mfma_f32_16x16x32_bf16 v[102:105], v[192:195], v[174:177], v[102:105]
	v_mfma_f32_16x16x32_bf16 v[106:109], v[208:211], v[174:177], v[106:109]
	v_mfma_f32_16x16x32_bf16 v[110:113], v[212:215], v[174:177], v[110:113]
	v_mfma_f32_16x16x32_bf16 v[114:117], v[188:191], v[182:185], v[114:117]
	v_mfma_f32_16x16x32_bf16 v[118:121], v[192:195], v[182:185], v[118:121]
	v_mfma_f32_16x16x32_bf16 v[122:125], v[208:211], v[182:185], v[122:125]
	v_mfma_f32_16x16x32_bf16 v[126:129], v[212:215], v[182:185], v[126:129]
	s_waitcnt vmcnt(0)
	s_barrier
	ds_read_b128 v[148:151], v140 offset:0
	ds_read_b128 v[152:155], v140 offset:2048
	ds_read_b128 v[156:159], v140 offset:4096
	ds_read_b128 v[160:163], v140 offset:6144
	ds_read_b128 v[164:167], v140 offset:16384
	ds_read_b128 v[168:171], v140 offset:18432
	ds_read_b128 v[174:177], v140 offset:20480
	ds_read_b128 v[182:185], v140 offset:22528
	ds_read_b128 v[188:191], v142 offset:49152
	ds_read_b128 v[192:195], v142 offset:51200
	ds_read_b128 v[208:211], v142 offset:53248
	ds_read_b128 v[212:215], v142 offset:55296
	s_waitcnt lgkmcnt(0)
	v_mfma_f32_16x16x32_bf16 v[62:65], v[188:191], v[148:151], v[62:65]
	v_mfma_f32_16x16x32_bf16 v[58:61], v[192:195], v[148:151], v[58:61]
	v_mfma_f32_16x16x32_bf16 v[54:57], v[208:211], v[148:151], v[54:57]
	v_mfma_f32_16x16x32_bf16 v[50:53], v[212:215], v[148:151], v[50:53]
	v_mfma_f32_16x16x32_bf16 v[46:49], v[188:191], v[152:155], v[46:49]
	v_mfma_f32_16x16x32_bf16 v[42:45], v[192:195], v[152:155], v[42:45]
	v_mfma_f32_16x16x32_bf16 v[38:41], v[208:211], v[152:155], v[38:41]
	v_mfma_f32_16x16x32_bf16 v[34:37], v[212:215], v[152:155], v[34:37]
	v_mfma_f32_16x16x32_bf16 v[30:33], v[188:191], v[156:159], v[30:33]
	v_mfma_f32_16x16x32_bf16 v[26:29], v[192:195], v[156:159], v[26:29]
	v_mfma_f32_16x16x32_bf16 v[22:25], v[208:211], v[156:159], v[22:25]
	v_mfma_f32_16x16x32_bf16 v[18:21], v[212:215], v[156:159], v[18:21]
	v_mfma_f32_16x16x32_bf16 v[14:17], v[188:191], v[160:163], v[14:17]
	v_mfma_f32_16x16x32_bf16 v[10:13], v[192:195], v[160:163], v[10:13]
	v_mfma_f32_16x16x32_bf16 v[6:9], v[208:211], v[160:163], v[6:9]
	v_mfma_f32_16x16x32_bf16 v[2:5], v[212:215], v[160:163], v[2:5]
	v_mfma_f32_16x16x32_bf16 v[66:69], v[188:191], v[164:167], v[66:69]
	v_mfma_f32_16x16x32_bf16 v[70:73], v[192:195], v[164:167], v[70:73]
	v_mfma_f32_16x16x32_bf16 v[74:77], v[208:211], v[164:167], v[74:77]
	v_mfma_f32_16x16x32_bf16 v[78:81], v[212:215], v[164:167], v[78:81]
	v_mfma_f32_16x16x32_bf16 v[82:85], v[188:191], v[168:171], v[82:85]
	v_mfma_f32_16x16x32_bf16 v[86:89], v[192:195], v[168:171], v[86:89]
	v_mfma_f32_16x16x32_bf16 v[90:93], v[208:211], v[168:171], v[90:93]
	v_mfma_f32_16x16x32_bf16 v[94:97], v[212:215], v[168:171], v[94:97]
	v_mfma_f32_16x16x32_bf16 v[98:101], v[188:191], v[174:177], v[98:101]
	v_mfma_f32_16x16x32_bf16 v[102:105], v[192:195], v[174:177], v[102:105]
	v_mfma_f32_16x16x32_bf16 v[106:109], v[208:211], v[174:177], v[106:109]
	v_mfma_f32_16x16x32_bf16 v[110:113], v[212:215], v[174:177], v[110:113]
	v_mfma_f32_16x16x32_bf16 v[114:117], v[188:191], v[182:185], v[114:117]
	v_mfma_f32_16x16x32_bf16 v[118:121], v[192:195], v[182:185], v[118:121]
	v_mfma_f32_16x16x32_bf16 v[122:125], v[208:211], v[182:185], v[122:125]
	v_mfma_f32_16x16x32_bf16 v[126:129], v[212:215], v[182:185], v[126:129]
	ds_read_b128 v[148:151], v141 offset:0
	ds_read_b128 v[152:155], v141 offset:2048
	ds_read_b128 v[156:159], v141 offset:4096
	ds_read_b128 v[160:163], v141 offset:6144
	ds_read_b128 v[164:167], v141 offset:16384
	ds_read_b128 v[168:171], v141 offset:18432
	ds_read_b128 v[174:177], v141 offset:20480
	ds_read_b128 v[182:185], v141 offset:22528
	ds_read_b128 v[188:191], v143 offset:49152
	ds_read_b128 v[192:195], v143 offset:51200
	ds_read_b128 v[208:211], v143 offset:53248
	ds_read_b128 v[212:215], v143 offset:55296
	s_waitcnt lgkmcnt(0)
	v_mfma_f32_16x16x32_bf16 v[62:65], v[188:191], v[148:151], v[62:65]
	v_mfma_f32_16x16x32_bf16 v[58:61], v[192:195], v[148:151], v[58:61]
	v_mfma_f32_16x16x32_bf16 v[54:57], v[208:211], v[148:151], v[54:57]
	v_mfma_f32_16x16x32_bf16 v[50:53], v[212:215], v[148:151], v[50:53]
	v_mfma_f32_16x16x32_bf16 v[46:49], v[188:191], v[152:155], v[46:49]
	v_mfma_f32_16x16x32_bf16 v[42:45], v[192:195], v[152:155], v[42:45]
	v_mfma_f32_16x16x32_bf16 v[38:41], v[208:211], v[152:155], v[38:41]
	v_mfma_f32_16x16x32_bf16 v[34:37], v[212:215], v[152:155], v[34:37]
	v_mfma_f32_16x16x32_bf16 v[30:33], v[188:191], v[156:159], v[30:33]
	v_mfma_f32_16x16x32_bf16 v[26:29], v[192:195], v[156:159], v[26:29]
	v_mfma_f32_16x16x32_bf16 v[22:25], v[208:211], v[156:159], v[22:25]
	v_mfma_f32_16x16x32_bf16 v[18:21], v[212:215], v[156:159], v[18:21]
	v_mfma_f32_16x16x32_bf16 v[14:17], v[188:191], v[160:163], v[14:17]
	v_mfma_f32_16x16x32_bf16 v[10:13], v[192:195], v[160:163], v[10:13]
	v_mfma_f32_16x16x32_bf16 v[6:9], v[208:211], v[160:163], v[6:9]
	v_mfma_f32_16x16x32_bf16 v[2:5], v[212:215], v[160:163], v[2:5]
	v_mfma_f32_16x16x32_bf16 v[66:69], v[188:191], v[164:167], v[66:69]
	v_mfma_f32_16x16x32_bf16 v[70:73], v[192:195], v[164:167], v[70:73]
	v_mfma_f32_16x16x32_bf16 v[74:77], v[208:211], v[164:167], v[74:77]
	v_mfma_f32_16x16x32_bf16 v[78:81], v[212:215], v[164:167], v[78:81]
	v_mfma_f32_16x16x32_bf16 v[82:85], v[188:191], v[168:171], v[82:85]
	v_mfma_f32_16x16x32_bf16 v[86:89], v[192:195], v[168:171], v[86:89]
	v_mfma_f32_16x16x32_bf16 v[90:93], v[208:211], v[168:171], v[90:93]
	v_mfma_f32_16x16x32_bf16 v[94:97], v[212:215], v[168:171], v[94:97]
	v_mfma_f32_16x16x32_bf16 v[98:101], v[188:191], v[174:177], v[98:101]
	v_mfma_f32_16x16x32_bf16 v[102:105], v[192:195], v[174:177], v[102:105]
	v_mfma_f32_16x16x32_bf16 v[106:109], v[208:211], v[174:177], v[106:109]
	v_mfma_f32_16x16x32_bf16 v[110:113], v[212:215], v[174:177], v[110:113]
	v_mfma_f32_16x16x32_bf16 v[114:117], v[188:191], v[182:185], v[114:117]
	v_mfma_f32_16x16x32_bf16 v[118:121], v[192:195], v[182:185], v[118:121]
	v_mfma_f32_16x16x32_bf16 v[122:125], v[208:211], v[182:185], v[122:125]
	v_mfma_f32_16x16x32_bf16 v[126:129], v[212:215], v[182:185], v[126:129]
	v_lshrrev_b32_e32 v144, 7, v196
	v_and_b32_e32 v145, 15, v196
	v_lshl_or_b32 v144, v144, 6, v145
	v_lshlrev_b32_e32 v144, 12, v144
	v_bfe_u32 v145, v196, 6, 1
	v_bfe_u32 v146, v196, 4, 2
	v_lshlrev_b32_e32 v145, 8, v145
	v_lshl_or_b32 v145, v146, 4, v145
	v_add_u32_e32 v136, v144, v145
	v_add_u32_e32 v137, 0x10000, v136
	v_add_u32_e32 v138, 0x20000, v136
	v_add_u32_e32 v139, 0x30000, v136
	s_nop 7
	s_nop 7
	s_nop 7
	global_load_dwordx4 v[148:151], v136, s[50:51] offset:0
	global_load_dwordx4 v[152:155], v136, s[50:51] offset:64
	global_load_dwordx4 v[156:159], v136, s[50:51] offset:128
	global_load_dwordx4 v[160:163], v136, s[50:51] offset:192
	global_load_dwordx4 v[164:167], v137, s[50:51] offset:0
	global_load_dwordx4 v[168:171], v137, s[50:51] offset:64
	global_load_dwordx4 v[174:177], v137, s[50:51] offset:128
	global_load_dwordx4 v[182:185], v137, s[50:51] offset:192
	global_load_dwordx4 v[188:191], v138, s[50:51] offset:0
	global_load_dwordx4 v[192:195], v138, s[50:51] offset:64
	global_load_dwordx4 v[208:211], v138, s[50:51] offset:128
	global_load_dwordx4 v[212:215], v138, s[50:51] offset:192
	global_load_dwordx4 v[216:219], v139, s[50:51] offset:0
	global_load_dwordx4 v[220:223], v139, s[50:51] offset:64
	global_load_dwordx4 v[242:245], v139, s[50:51] offset:128
	global_load_dwordx4 v[144:147], v139, s[50:51] offset:192
	s_waitcnt vmcnt(0)
	v_pk_add_f32 v[62:63], v[62:63], v[148:149]
	v_pk_add_f32 v[64:65], v[64:65], v[150:151]
	v_pk_add_f32 v[58:59], v[58:59], v[152:153]
	v_pk_add_f32 v[60:61], v[60:61], v[154:155]
	v_pk_add_f32 v[54:55], v[54:55], v[156:157]
	v_pk_add_f32 v[56:57], v[56:57], v[158:159]
	v_pk_add_f32 v[50:51], v[50:51], v[160:161]
	v_pk_add_f32 v[52:53], v[52:53], v[162:163]
	v_pk_add_f32 v[46:47], v[46:47], v[164:165]
	v_pk_add_f32 v[48:49], v[48:49], v[166:167]
	v_pk_add_f32 v[42:43], v[42:43], v[168:169]
	v_pk_add_f32 v[44:45], v[44:45], v[170:171]
	v_pk_add_f32 v[38:39], v[38:39], v[174:175]
	v_pk_add_f32 v[40:41], v[40:41], v[176:177]
	v_pk_add_f32 v[34:35], v[34:35], v[182:183]
	v_pk_add_f32 v[36:37], v[36:37], v[184:185]
	v_pk_add_f32 v[30:31], v[30:31], v[188:189]
	v_pk_add_f32 v[32:33], v[32:33], v[190:191]
	v_pk_add_f32 v[26:27], v[26:27], v[192:193]
	v_pk_add_f32 v[28:29], v[28:29], v[194:195]
	v_pk_add_f32 v[22:23], v[22:23], v[208:209]
	v_pk_add_f32 v[24:25], v[24:25], v[210:211]
	v_pk_add_f32 v[18:19], v[18:19], v[212:213]
	v_pk_add_f32 v[20:21], v[20:21], v[214:215]
	v_pk_add_f32 v[14:15], v[14:15], v[216:217]
	v_pk_add_f32 v[16:17], v[16:17], v[218:219]
	v_pk_add_f32 v[10:11], v[10:11], v[220:221]
	v_pk_add_f32 v[12:13], v[12:13], v[222:223]
	v_pk_add_f32 v[6:7], v[6:7], v[242:243]
	v_pk_add_f32 v[8:9], v[8:9], v[244:245]
	v_pk_add_f32 v[2:3], v[2:3], v[144:145]
	v_pk_add_f32 v[4:5], v[4:5], v[146:147]
	global_load_dwordx4 v[148:151], v136, s[52:53] offset:0
	global_load_dwordx4 v[152:155], v136, s[52:53] offset:64
	global_load_dwordx4 v[156:159], v136, s[52:53] offset:128
	global_load_dwordx4 v[160:163], v136, s[52:53] offset:192
	global_load_dwordx4 v[164:167], v137, s[52:53] offset:0
	global_load_dwordx4 v[168:171], v137, s[52:53] offset:64
	global_load_dwordx4 v[174:177], v137, s[52:53] offset:128
	global_load_dwordx4 v[182:185], v137, s[52:53] offset:192
	global_load_dwordx4 v[188:191], v138, s[52:53] offset:0
	global_load_dwordx4 v[192:195], v138, s[52:53] offset:64
	global_load_dwordx4 v[208:211], v138, s[52:53] offset:128
	global_load_dwordx4 v[212:215], v138, s[52:53] offset:192
	global_load_dwordx4 v[216:219], v139, s[52:53] offset:0
	global_load_dwordx4 v[220:223], v139, s[52:53] offset:64
	global_load_dwordx4 v[242:245], v139, s[52:53] offset:128
	global_load_dwordx4 v[144:147], v139, s[52:53] offset:192
	global_store_dwordx4 v136, v[62:65], s[40:41] offset:0
	global_store_dwordx4 v136, v[58:61], s[40:41] offset:64
	global_store_dwordx4 v136, v[54:57], s[40:41] offset:128
	global_store_dwordx4 v136, v[50:53], s[40:41] offset:192
	global_store_dwordx4 v137, v[46:49], s[40:41] offset:0
	global_store_dwordx4 v137, v[42:45], s[40:41] offset:64
	global_store_dwordx4 v137, v[38:41], s[40:41] offset:128
	global_store_dwordx4 v137, v[34:37], s[40:41] offset:192
	global_store_dwordx4 v138, v[30:33], s[40:41] offset:0
	global_store_dwordx4 v138, v[26:29], s[40:41] offset:64
	global_store_dwordx4 v138, v[22:25], s[40:41] offset:128
	global_store_dwordx4 v138, v[18:21], s[40:41] offset:192
	global_store_dwordx4 v139, v[14:17], s[40:41] offset:0
	global_store_dwordx4 v139, v[10:13], s[40:41] offset:64
	global_store_dwordx4 v139, v[6:9], s[40:41] offset:128
	global_store_dwordx4 v139, v[2:5], s[40:41] offset:192
	s_waitcnt vmcnt(0)
	v_pk_add_f32 v[66:67], v[66:67], v[148:149]
	v_pk_add_f32 v[68:69], v[68:69], v[150:151]
	v_pk_add_f32 v[70:71], v[70:71], v[152:153]
	v_pk_add_f32 v[72:73], v[72:73], v[154:155]
	v_pk_add_f32 v[74:75], v[74:75], v[156:157]
	v_pk_add_f32 v[76:77], v[76:77], v[158:159]
	v_pk_add_f32 v[78:79], v[78:79], v[160:161]
	v_pk_add_f32 v[80:81], v[80:81], v[162:163]
	v_pk_add_f32 v[82:83], v[82:83], v[164:165]
	v_pk_add_f32 v[84:85], v[84:85], v[166:167]
	v_pk_add_f32 v[86:87], v[86:87], v[168:169]
	v_pk_add_f32 v[88:89], v[88:89], v[170:171]
	v_pk_add_f32 v[90:91], v[90:91], v[174:175]
	v_pk_add_f32 v[92:93], v[92:93], v[176:177]
	v_pk_add_f32 v[94:95], v[94:95], v[182:183]
	v_pk_add_f32 v[96:97], v[96:97], v[184:185]
	v_pk_add_f32 v[98:99], v[98:99], v[188:189]
	v_pk_add_f32 v[100:101], v[100:101], v[190:191]
	v_pk_add_f32 v[102:103], v[102:103], v[192:193]
	v_pk_add_f32 v[104:105], v[104:105], v[194:195]
	v_pk_add_f32 v[106:107], v[106:107], v[208:209]
	v_pk_add_f32 v[108:109], v[108:109], v[210:211]
	v_pk_add_f32 v[110:111], v[110:111], v[212:213]
	v_pk_add_f32 v[112:113], v[112:113], v[214:215]
	v_pk_add_f32 v[114:115], v[114:115], v[216:217]
	v_pk_add_f32 v[116:117], v[116:117], v[218:219]
	v_pk_add_f32 v[118:119], v[118:119], v[220:221]
	v_pk_add_f32 v[120:121], v[120:121], v[222:223]
	v_pk_add_f32 v[122:123], v[122:123], v[242:243]
	v_pk_add_f32 v[124:125], v[124:125], v[244:245]
	v_pk_add_f32 v[126:127], v[126:127], v[144:145]
	v_pk_add_f32 v[128:129], v[128:129], v[146:147]
	global_store_dwordx4 v136, v[66:69], s[42:43] offset:0
	global_store_dwordx4 v136, v[70:73], s[42:43] offset:64
	global_store_dwordx4 v136, v[74:77], s[42:43] offset:128
	global_store_dwordx4 v136, v[78:81], s[42:43] offset:192
	global_store_dwordx4 v137, v[82:85], s[42:43] offset:0
	global_store_dwordx4 v137, v[86:89], s[42:43] offset:64
	global_store_dwordx4 v137, v[90:93], s[42:43] offset:128
	global_store_dwordx4 v137, v[94:97], s[42:43] offset:192
	global_store_dwordx4 v138, v[98:101], s[42:43] offset:0
	global_store_dwordx4 v138, v[102:105], s[42:43] offset:64
	global_store_dwordx4 v138, v[106:109], s[42:43] offset:128
	global_store_dwordx4 v138, v[110:113], s[42:43] offset:192
	global_store_dwordx4 v139, v[114:117], s[42:43] offset:0
	global_store_dwordx4 v139, v[118:121], s[42:43] offset:64
	global_store_dwordx4 v139, v[122:125], s[42:43] offset:128
	global_store_dwordx4 v139, v[126:129], s[42:43] offset:192
	s_branch .LBB0_2211

.Lf2_k:
	s_waitcnt vmcnt(0)
	s_barrier
	s_add_i32 m0, s64, 0xc000
	s_nop 0
	global_load_lds_dwordx4 v76, s[58:59]
	s_add_i32 m0, s64, 0xd000
	s_nop 0
	global_load_lds_dwordx4 v77, s[58:59]
	s_add_i32 m0, s64, 0xe000
	s_nop 0
	global_load_lds_dwordx4 v78, s[58:59]
	s_add_i32 m0, s64, 0xf000
	s_nop 0
	global_load_lds_dwordx4 v79, s[58:59]
	s_add_u32 s58, s58, 0x80
	s_addc_u32 s59, s59, 0
	ds_read_b128 v[148:151], v80 offset:0
	ds_read_b128 v[152:155], v80 offset:2048
	ds_read_b128 v[156:159], v80 offset:4096
	ds_read_b128 v[160:163], v80 offset:6144
	ds_read_b128 v[188:191], v144 offset:32768
	ds_read_b128 v[192:195], v144 offset:34816
	ds_read_b128 v[208:211], v144 offset:36864
	ds_read_b128 v[212:215], v144 offset:38912
	ds_read_b128 v[164:167], v80 offset:16384
	ds_read_b128 v[168:171], v80 offset:18432
	ds_read_b128 v[174:177], v80 offset:20480
	ds_read_b128 v[182:185], v80 offset:22528
	s_waitcnt lgkmcnt(4)
	v_mfma_f32_16x16x32_bf16 v[62:65], v[188:191], v[148:151], v[62:65]
	v_mfma_f32_16x16x32_bf16 v[54:57], v[192:195], v[148:151], v[54:57]
	v_mfma_f32_16x16x32_bf16 v[58:61], v[208:211], v[148:151], v[58:61]
	v_mfma_f32_16x16x32_bf16 v[50:53], v[212:215], v[148:151], v[50:53]
	v_mfma_f32_16x16x32_bf16 v[46:49], v[188:191], v[152:155], v[46:49]
	v_mfma_f32_16x16x32_bf16 v[38:41], v[192:195], v[152:155], v[38:41]
	v_mfma_f32_16x16x32_bf16 v[42:45], v[208:211], v[152:155], v[42:45]
	v_mfma_f32_16x16x32_bf16 v[34:37], v[212:215], v[152:155], v[34:37]
	v_mfma_f32_16x16x32_bf16 v[30:33], v[188:191], v[156:159], v[30:33]
	v_mfma_f32_16x16x32_bf16 v[22:25], v[192:195], v[156:159], v[22:25]
	v_mfma_f32_16x16x32_bf16 v[26:29], v[208:211], v[156:159], v[26:29]
	v_mfma_f32_16x16x32_bf16 v[18:21], v[212:215], v[156:159], v[18:21]
	v_mfma_f32_16x16x32_bf16 v[14:17], v[188:191], v[160:163], v[14:17]
	v_mfma_f32_16x16x32_bf16 v[6:9], v[192:195], v[160:163], v[6:9]
	v_mfma_f32_16x16x32_bf16 v[10:13], v[208:211], v[160:163], v[10:13]
	v_mfma_f32_16x16x32_bf16 v[2:5], v[212:215], v[160:163], v[2:5]
	s_waitcnt lgkmcnt(0)
	v_mfma_f32_16x16x32_bf16 v[66:69], v[188:191], v[164:167], v[66:69]
	v_mfma_f32_16x16x32_bf16 v[70:73], v[192:195], v[164:167], v[70:73]
	v_mfma_f32_16x16x32_bf16 v[82:85], v[208:211], v[164:167], v[82:85]
	v_mfma_f32_16x16x32_bf16 v[86:89], v[212:215], v[164:167], v[86:89]
	v_mfma_f32_16x16x32_bf16 v[90:93], v[188:191], v[168:171], v[90:93]
	v_mfma_f32_16x16x32_bf16 v[94:97], v[192:195], v[168:171], v[94:97]
	v_mfma_f32_16x16x32_bf16 v[98:101], v[208:211], v[168:171], v[98:101]
	v_mfma_f32_16x16x32_bf16 v[102:105], v[212:215], v[168:171], v[102:105]
	v_mfma_f32_16x16x32_bf16 v[106:109], v[188:191], v[174:177], v[106:109]
	v_mfma_f32_16x16x32_bf16 v[110:113], v[192:195], v[174:177], v[110:113]
	v_mfma_f32_16x16x32_bf16 v[114:117], v[208:211], v[174:177], v[114:117]
	v_mfma_f32_16x16x32_bf16 v[118:121], v[212:215], v[174:177], v[118:121]
	v_mfma_f32_16x16x32_bf16 v[122:125], v[188:191], v[182:185], v[122:125]
	v_mfma_f32_16x16x32_bf16 v[126:129], v[192:195], v[182:185], v[126:129]
	v_mfma_f32_16x16x32_bf16 v[136:139], v[208:211], v[182:185], v[136:139]
	v_mfma_f32_16x16x32_bf16 v[140:143], v[212:215], v[182:185], v[140:143]
	ds_read_b128 v[148:151], v81 offset:0
	ds_read_b128 v[152:155], v81 offset:2048
	ds_read_b128 v[156:159], v81 offset:4096
	ds_read_b128 v[160:163], v81 offset:6144
	ds_read_b128 v[188:191], v145 offset:32768
	ds_read_b128 v[192:195], v145 offset:34816
	ds_read_b128 v[208:211], v145 offset:36864
	ds_read_b128 v[212:215], v145 offset:38912
	ds_read_b128 v[164:167], v81 offset:16384
	ds_read_b128 v[168:171], v81 offset:18432
	ds_read_b128 v[174:177], v81 offset:20480
	ds_read_b128 v[182:185], v81 offset:22528
	s_waitcnt lgkmcnt(0)
	s_barrier
	s_add_i32 m0, s64, 0x0
	s_nop 0
	global_load_lds_dwordx4 v76, s[50:51]
	s_add_i32 m0, s64, 0x1000
	s_nop 0
	global_load_lds_dwordx4 v77, s[50:51]
	s_add_i32 m0, s64, 0x2000
	s_nop 0
	global_load_lds_dwordx4 v78, s[50:51]
	s_add_i32 m0, s64, 0x3000
	s_nop 0
	global_load_lds_dwordx4 v79, s[50:51]
	s_add_i32 m0, s64, 0x4000
	s_nop 0
	global_load_lds_dwordx4 v76, s[52:53]
	s_add_i32 m0, s64, 0x5000
	s_nop 0
	global_load_lds_dwordx4 v77, s[52:53]
	s_add_i32 m0, s64, 0x6000
	s_nop 0
	global_load_lds_dwordx4 v78, s[52:53]
	s_add_i32 m0, s64, 0x7000
	s_nop 0
	global_load_lds_dwordx4 v79, s[52:53]
	s_add_u32 s50, s50, 0x80
	s_addc_u32 s51, s51, 0
	s_add_u32 s52, s52, 0x80
	s_addc_u32 s53, s53, 0
	v_mfma_f32_16x16x32_bf16 v[62:65], v[188:191], v[148:151], v[62:65]
	v_mfma_f32_16x16x32_bf16 v[54:57], v[192:195], v[148:151], v[54:57]
	v_mfma_f32_16x16x32_bf16 v[58:61], v[208:211], v[148:151], v[58:61]
	v_mfma_f32_16x16x32_bf16 v[50:53], v[212:215], v[148:151], v[50:53]
	v_mfma_f32_16x16x32_bf16 v[46:49], v[188:191], v[152:155], v[46:49]
	v_mfma_f32_16x16x32_bf16 v[38:41], v[192:195], v[152:155], v[38:41]
	v_mfma_f32_16x16x32_bf16 v[42:45], v[208:211], v[152:155], v[42:45]
	v_mfma_f32_16x16x32_bf16 v[34:37], v[212:215], v[152:155], v[34:37]
	v_mfma_f32_16x16x32_bf16 v[30:33], v[188:191], v[156:159], v[30:33]
	v_mfma_f32_16x16x32_bf16 v[22:25], v[192:195], v[156:159], v[22:25]
	v_mfma_f32_16x16x32_bf16 v[26:29], v[208:211], v[156:159], v[26:29]
	v_mfma_f32_16x16x32_bf16 v[18:21], v[212:215], v[156:159], v[18:21]
	v_mfma_f32_16x16x32_bf16 v[14:17], v[188:191], v[160:163], v[14:17]
	v_mfma_f32_16x16x32_bf16 v[6:9], v[192:195], v[160:163], v[6:9]
	v_mfma_f32_16x16x32_bf16 v[10:13], v[208:211], v[160:163], v[10:13]
	v_mfma_f32_16x16x32_bf16 v[2:5], v[212:215], v[160:163], v[2:5]
	v_mfma_f32_16x16x32_bf16 v[66:69], v[188:191], v[164:167], v[66:69]
	v_mfma_f32_16x16x32_bf16 v[70:73], v[192:195], v[164:167], v[70:73]
	v_mfma_f32_16x16x32_bf16 v[82:85], v[208:211], v[164:167], v[82:85]
	v_mfma_f32_16x16x32_bf16 v[86:89], v[212:215], v[164:167], v[86:89]
	v_mfma_f32_16x16x32_bf16 v[90:93], v[188:191], v[168:171], v[90:93]
	v_mfma_f32_16x16x32_bf16 v[94:97], v[192:195], v[168:171], v[94:97]
	v_mfma_f32_16x16x32_bf16 v[98:101], v[208:211], v[168:171], v[98:101]
	v_mfma_f32_16x16x32_bf16 v[102:105], v[212:215], v[168:171], v[102:105]
	v_mfma_f32_16x16x32_bf16 v[106:109], v[188:191], v[174:177], v[106:109]
	v_mfma_f32_16x16x32_bf16 v[110:113], v[192:195], v[174:177], v[110:113]
	v_mfma_f32_16x16x32_bf16 v[114:117], v[208:211], v[174:177], v[114:117]
	v_mfma_f32_16x16x32_bf16 v[118:121], v[212:215], v[174:177], v[118:121]
	v_mfma_f32_16x16x32_bf16 v[122:125], v[188:191], v[182:185], v[122:125]
	v_mfma_f32_16x16x32_bf16 v[126:129], v[192:195], v[182:185], v[126:129]
	v_mfma_f32_16x16x32_bf16 v[136:139], v[208:211], v[182:185], v[136:139]
	v_mfma_f32_16x16x32_bf16 v[140:143], v[212:215], v[182:185], v[140:143]
	s_waitcnt vmcnt(0)
	s_barrier
	s_add_i32 m0, s64, 0x8000
	s_nop 0
	global_load_lds_dwordx4 v76, s[58:59]
	s_add_i32 m0, s64, 0x9000
	s_nop 0
	global_load_lds_dwordx4 v77, s[58:59]
	s_add_i32 m0, s64, 0xa000
	s_nop 0
	global_load_lds_dwordx4 v78, s[58:59]
	s_add_i32 m0, s64, 0xb000
	s_nop 0
	global_load_lds_dwordx4 v79, s[58:59]
	s_add_u32 s58, s58, 0x80
	s_addc_u32 s59, s59, 0
	ds_read_b128 v[148:151], v80 offset:0
	ds_read_b128 v[152:155], v80 offset:2048
	ds_read_b128 v[156:159], v80 offset:4096
	ds_read_b128 v[160:163], v80 offset:6144
	ds_read_b128 v[188:191], v144 offset:49152
	ds_read_b128 v[192:195], v144 offset:51200
	ds_read_b128 v[208:211], v144 offset:53248
	ds_read_b128 v[212:215], v144 offset:55296
	ds_read_b128 v[164:167], v80 offset:16384
	ds_read_b128 v[168:171], v80 offset:18432
	ds_read_b128 v[174:177], v80 offset:20480
	ds_read_b128 v[182:185], v80 offset:22528
	s_waitcnt lgkmcnt(4)
	v_mfma_f32_16x16x32_bf16 v[62:65], v[188:191], v[148:151], v[62:65]
	v_mfma_f32_16x16x32_bf16 v[54:57], v[192:195], v[148:151], v[54:57]
	v_mfma_f32_16x16x32_bf16 v[58:61], v[208:211], v[148:151], v[58:61]
	v_mfma_f32_16x16x32_bf16 v[50:53], v[212:215], v[148:151], v[50:53]
	v_mfma_f32_16x16x32_bf16 v[46:49], v[188:191], v[152:155], v[46:49]
	v_mfma_f32_16x16x32_bf16 v[38:41], v[192:195], v[152:155], v[38:41]
	v_mfma_f32_16x16x32_bf16 v[42:45], v[208:211], v[152:155], v[42:45]
	v_mfma_f32_16x16x32_bf16 v[34:37], v[212:215], v[152:155], v[34:37]
	v_mfma_f32_16x16x32_bf16 v[30:33], v[188:191], v[156:159], v[30:33]
	v_mfma_f32_16x16x32_bf16 v[22:25], v[192:195], v[156:159], v[22:25]
	v_mfma_f32_16x16x32_bf16 v[26:29], v[208:211], v[156:159], v[26:29]
	v_mfma_f32_16x16x32_bf16 v[18:21], v[212:215], v[156:159], v[18:21]
	v_mfma_f32_16x16x32_bf16 v[14:17], v[188:191], v[160:163], v[14:17]
	v_mfma_f32_16x16x32_bf16 v[6:9], v[192:195], v[160:163], v[6:9]
	v_mfma_f32_16x16x32_bf16 v[10:13], v[208:211], v[160:163], v[10:13]
	v_mfma_f32_16x16x32_bf16 v[2:5], v[212:215], v[160:163], v[2:5]
	s_waitcnt lgkmcnt(0)
	v_mfma_f32_16x16x32_bf16 v[66:69], v[188:191], v[164:167], v[66:69]
	v_mfma_f32_16x16x32_bf16 v[70:73], v[192:195], v[164:167], v[70:73]
	v_mfma_f32_16x16x32_bf16 v[82:85], v[208:211], v[164:167], v[82:85]
	v_mfma_f32_16x16x32_bf16 v[86:89], v[212:215], v[164:167], v[86:89]
	v_mfma_f32_16x16x32_bf16 v[90:93], v[188:191], v[168:171], v[90:93]
	v_mfma_f32_16x16x32_bf16 v[94:97], v[192:195], v[168:171], v[94:97]
	v_mfma_f32_16x16x32_bf16 v[98:101], v[208:211], v[168:171], v[98:101]
	v_mfma_f32_16x16x32_bf16 v[102:105], v[212:215], v[168:171], v[102:105]
	v_mfma_f32_16x16x32_bf16 v[106:109], v[188:191], v[174:177], v[106:109]
	v_mfma_f32_16x16x32_bf16 v[110:113], v[192:195], v[174:177], v[110:113]
	v_mfma_f32_16x16x32_bf16 v[114:117], v[208:211], v[174:177], v[114:117]
	v_mfma_f32_16x16x32_bf16 v[118:121], v[212:215], v[174:177], v[118:121]
	v_mfma_f32_16x16x32_bf16 v[122:125], v[188:191], v[182:185], v[122:125]
	v_mfma_f32_16x16x32_bf16 v[126:129], v[192:195], v[182:185], v[126:129]
	v_mfma_f32_16x16x32_bf16 v[136:139], v[208:211], v[182:185], v[136:139]
	v_mfma_f32_16x16x32_bf16 v[140:143], v[212:215], v[182:185], v[140:143]
	ds_read_b128 v[148:151], v81 offset:0
	ds_read_b128 v[152:155], v81 offset:2048
	ds_read_b128 v[156:159], v81 offset:4096
	ds_read_b128 v[160:163], v81 offset:6144
	ds_read_b128 v[188:191], v145 offset:49152
	ds_read_b128 v[192:195], v145 offset:51200
	ds_read_b128 v[208:211], v145 offset:53248
	ds_read_b128 v[212:215], v145 offset:55296
	ds_read_b128 v[164:167], v81 offset:16384
	ds_read_b128 v[168:171], v81 offset:18432
	ds_read_b128 v[174:177], v81 offset:20480
	ds_read_b128 v[182:185], v81 offset:22528
	s_waitcnt lgkmcnt(0)
	s_barrier
	s_add_i32 m0, s64, 0x0
	s_nop 0
	global_load_lds_dwordx4 v76, s[50:51]
	s_add_i32 m0, s64, 0x1000
	s_nop 0
	global_load_lds_dwordx4 v77, s[50:51]
	s_add_i32 m0, s64, 0x2000
	s_nop 0
	global_load_lds_dwordx4 v78, s[50:51]
	s_add_i32 m0, s64, 0x3000
	s_nop 0
	global_load_lds_dwordx4 v79, s[50:51]
	s_add_i32 m0, s64, 0x4000
	s_nop 0
	global_load_lds_dwordx4 v76, s[52:53]
	s_add_i32 m0, s64, 0x5000
	s_nop 0
	global_load_lds_dwordx4 v77, s[52:53]
	s_add_i32 m0, s64, 0x6000
	s_nop 0
	global_load_lds_dwordx4 v78, s[52:53]
	s_add_i32 m0, s64, 0x7000
	s_nop 0
	global_load_lds_dwordx4 v79, s[52:53]
	s_add_u32 s50, s50, 0x80
	s_addc_u32 s51, s51, 0
	s_add_u32 s52, s52, 0x80
	s_addc_u32 s53, s53, 0
	v_mfma_f32_16x16x32_bf16 v[62:65], v[188:191], v[148:151], v[62:65]
	v_mfma_f32_16x16x32_bf16 v[54:57], v[192:195], v[148:151], v[54:57]
	v_mfma_f32_16x16x32_bf16 v[58:61], v[208:211], v[148:151], v[58:61]
	v_mfma_f32_16x16x32_bf16 v[50:53], v[212:215], v[148:151], v[50:53]
	v_mfma_f32_16x16x32_bf16 v[46:49], v[188:191], v[152:155], v[46:49]
	v_mfma_f32_16x16x32_bf16 v[38:41], v[192:195], v[152:155], v[38:41]
	v_mfma_f32_16x16x32_bf16 v[42:45], v[208:211], v[152:155], v[42:45]
	v_mfma_f32_16x16x32_bf16 v[34:37], v[212:215], v[152:155], v[34:37]
	v_mfma_f32_16x16x32_bf16 v[30:33], v[188:191], v[156:159], v[30:33]
	v_mfma_f32_16x16x32_bf16 v[22:25], v[192:195], v[156:159], v[22:25]
	v_mfma_f32_16x16x32_bf16 v[26:29], v[208:211], v[156:159], v[26:29]
	v_mfma_f32_16x16x32_bf16 v[18:21], v[212:215], v[156:159], v[18:21]
	v_mfma_f32_16x16x32_bf16 v[14:17], v[188:191], v[160:163], v[14:17]
	v_mfma_f32_16x16x32_bf16 v[6:9], v[192:195], v[160:163], v[6:9]
	v_mfma_f32_16x16x32_bf16 v[10:13], v[208:211], v[160:163], v[10:13]
	v_mfma_f32_16x16x32_bf16 v[2:5], v[212:215], v[160:163], v[2:5]
	v_mfma_f32_16x16x32_bf16 v[66:69], v[188:191], v[164:167], v[66:69]
	v_mfma_f32_16x16x32_bf16 v[70:73], v[192:195], v[164:167], v[70:73]
	v_mfma_f32_16x16x32_bf16 v[82:85], v[208:211], v[164:167], v[82:85]
	v_mfma_f32_16x16x32_bf16 v[86:89], v[212:215], v[164:167], v[86:89]
	v_mfma_f32_16x16x32_bf16 v[90:93], v[188:191], v[168:171], v[90:93]
	v_mfma_f32_16x16x32_bf16 v[94:97], v[192:195], v[168:171], v[94:97]
	v_mfma_f32_16x16x32_bf16 v[98:101], v[208:211], v[168:171], v[98:101]
	v_mfma_f32_16x16x32_bf16 v[102:105], v[212:215], v[168:171], v[102:105]
	v_mfma_f32_16x16x32_bf16 v[106:109], v[188:191], v[174:177], v[106:109]
	v_mfma_f32_16x16x32_bf16 v[110:113], v[192:195], v[174:177], v[110:113]
	v_mfma_f32_16x16x32_bf16 v[114:117], v[208:211], v[174:177], v[114:117]
	v_mfma_f32_16x16x32_bf16 v[118:121], v[212:215], v[174:177], v[118:121]
	v_mfma_f32_16x16x32_bf16 v[122:125], v[188:191], v[182:185], v[122:125]
	v_mfma_f32_16x16x32_bf16 v[126:129], v[192:195], v[182:185], v[126:129]
	v_mfma_f32_16x16x32_bf16 v[136:139], v[208:211], v[182:185], v[136:139]
	v_mfma_f32_16x16x32_bf16 v[140:143], v[212:215], v[182:185], v[140:143]
	s_add_i32 s65, s65, -1
	s_cmp_lg_u32 s65, 0
	s_cbranch_scc1 .Lf2_k
	s_waitcnt vmcnt(0)
	s_barrier
	s_add_i32 m0, s64, 0xc000
	s_nop 0
	global_load_lds_dwordx4 v76, s[58:59]
	s_add_i32 m0, s64, 0xd000
	s_nop 0
	global_load_lds_dwordx4 v77, s[58:59]
	s_add_i32 m0, s64, 0xe000
	s_nop 0
	global_load_lds_dwordx4 v78, s[58:59]
	s_add_i32 m0, s64, 0xf000
	s_nop 0
	global_load_lds_dwordx4 v79, s[58:59]
	s_add_u32 s58, s58, 0x80
	s_addc_u32 s59, s59, 0
	ds_read_b128 v[148:151], v80 offset:0
	ds_read_b128 v[152:155], v80 offset:2048
	ds_read_b128 v[156:159], v80 offset:4096
	ds_read_b128 v[160:163], v80 offset:6144
	ds_read_b128 v[188:191], v144 offset:32768
	ds_read_b128 v[192:195], v144 offset:34816
	ds_read_b128 v[208:211], v144 offset:36864
	ds_read_b128 v[212:215], v144 offset:38912
	ds_read_b128 v[164:167], v80 offset:16384
	ds_read_b128 v[168:171], v80 offset:18432
	ds_read_b128 v[174:177], v80 offset:20480
	ds_read_b128 v[182:185], v80 offset:22528
	s_waitcnt lgkmcnt(4)
	v_mfma_f32_16x16x32_bf16 v[62:65], v[188:191], v[148:151], v[62:65]
	v_mfma_f32_16x16x32_bf16 v[54:57], v[192:195], v[148:151], v[54:57]
	v_mfma_f32_16x16x32_bf16 v[58:61], v[208:211], v[148:151], v[58:61]
	v_mfma_f32_16x16x32_bf16 v[50:53], v[212:215], v[148:151], v[50:53]
	v_mfma_f32_16x16x32_bf16 v[46:49], v[188:191], v[152:155], v[46:49]
	v_mfma_f32_16x16x32_bf16 v[38:41], v[192:195], v[152:155], v[38:41]
	v_mfma_f32_16x16x32_bf16 v[42:45], v[208:211], v[152:155], v[42:45]
	v_mfma_f32_16x16x32_bf16 v[34:37], v[212:215], v[152:155], v[34:37]
	v_mfma_f32_16x16x32_bf16 v[30:33], v[188:191], v[156:159], v[30:33]
	v_mfma_f32_16x16x32_bf16 v[22:25], v[192:195], v[156:159], v[22:25]
	v_mfma_f32_16x16x32_bf16 v[26:29], v[208:211], v[156:159], v[26:29]
	v_mfma_f32_16x16x32_bf16 v[18:21], v[212:215], v[156:159], v[18:21]
	v_mfma_f32_16x16x32_bf16 v[14:17], v[188:191], v[160:163], v[14:17]
	v_mfma_f32_16x16x32_bf16 v[6:9], v[192:195], v[160:163], v[6:9]
	v_mfma_f32_16x16x32_bf16 v[10:13], v[208:211], v[160:163], v[10:13]
	v_mfma_f32_16x16x32_bf16 v[2:5], v[212:215], v[160:163], v[2:5]
	s_waitcnt lgkmcnt(0)
	v_mfma_f32_16x16x32_bf16 v[66:69], v[188:191], v[164:167], v[66:69]
	v_mfma_f32_16x16x32_bf16 v[70:73], v[192:195], v[164:167], v[70:73]
	v_mfma_f32_16x16x32_bf16 v[82:85], v[208:211], v[164:167], v[82:85]
	v_mfma_f32_16x16x32_bf16 v[86:89], v[212:215], v[164:167], v[86:89]
	v_mfma_f32_16x16x32_bf16 v[90:93], v[188:191], v[168:171], v[90:93]
	v_mfma_f32_16x16x32_bf16 v[94:97], v[192:195], v[168:171], v[94:97]
	v_mfma_f32_16x16x32_bf16 v[98:101], v[208:211], v[168:171], v[98:101]
	v_mfma_f32_16x16x32_bf16 v[102:105], v[212:215], v[168:171], v[102:105]
	v_mfma_f32_16x16x32_bf16 v[106:109], v[188:191], v[174:177], v[106:109]
	v_mfma_f32_16x16x32_bf16 v[110:113], v[192:195], v[174:177], v[110:113]
	v_mfma_f32_16x16x32_bf16 v[114:117], v[208:211], v[174:177], v[114:117]
	v_mfma_f32_16x16x32_bf16 v[118:121], v[212:215], v[174:177], v[118:121]
	v_mfma_f32_16x16x32_bf16 v[122:125], v[188:191], v[182:185], v[122:125]
	v_mfma_f32_16x16x32_bf16 v[126:129], v[192:195], v[182:185], v[126:129]
	v_mfma_f32_16x16x32_bf16 v[136:139], v[208:211], v[182:185], v[136:139]
	v_mfma_f32_16x16x32_bf16 v[140:143], v[212:215], v[182:185], v[140:143]
	ds_read_b128 v[148:151], v81 offset:0
	ds_read_b128 v[152:155], v81 offset:2048
	ds_read_b128 v[156:159], v81 offset:4096
	ds_read_b128 v[160:163], v81 offset:6144
	ds_read_b128 v[188:191], v145 offset:32768
	ds_read_b128 v[192:195], v145 offset:34816
	ds_read_b128 v[208:211], v145 offset:36864
	ds_read_b128 v[212:215], v145 offset:38912
	ds_read_b128 v[164:167], v81 offset:16384
	ds_read_b128 v[168:171], v81 offset:18432
	ds_read_b128 v[174:177], v81 offset:20480
	ds_read_b128 v[182:185], v81 offset:22528
	s_waitcnt lgkmcnt(0)
	s_barrier
	s_add_i32 m0, s64, 0x0
	s_nop 0
	global_load_lds_dwordx4 v76, s[50:51]
	s_add_i32 m0, s64, 0x1000
	s_nop 0
	global_load_lds_dwordx4 v77, s[50:51]
	s_add_i32 m0, s64, 0x2000
	s_nop 0
	global_load_lds_dwordx4 v78, s[50:51]
	s_add_i32 m0, s64, 0x3000
	s_nop 0
	global_load_lds_dwordx4 v79, s[50:51]
	s_add_i32 m0, s64, 0x4000
	s_nop 0
	global_load_lds_dwordx4 v76, s[52:53]
	s_add_i32 m0, s64, 0x5000
	s_nop 0
	global_load_lds_dwordx4 v77, s[52:53]
	s_add_i32 m0, s64, 0x6000
	s_nop 0
	global_load_lds_dwordx4 v78, s[52:53]
	s_add_i32 m0, s64, 0x7000
	s_nop 0
	global_load_lds_dwordx4 v79, s[52:53]
	s_add_u32 s50, s50, 0x80
	s_addc_u32 s51, s51, 0
	s_add_u32 s52, s52, 0x80
	s_addc_u32 s53, s53, 0
	v_mfma_f32_16x16x32_bf16 v[62:65], v[188:191], v[148:151], v[62:65]
	v_mfma_f32_16x16x32_bf16 v[54:57], v[192:195], v[148:151], v[54:57]
	v_mfma_f32_16x16x32_bf16 v[58:61], v[208:211], v[148:151], v[58:61]
	v_mfma_f32_16x16x32_bf16 v[50:53], v[212:215], v[148:151], v[50:53]
	v_mfma_f32_16x16x32_bf16 v[46:49], v[188:191], v[152:155], v[46:49]
	v_mfma_f32_16x16x32_bf16 v[38:41], v[192:195], v[152:155], v[38:41]
	v_mfma_f32_16x16x32_bf16 v[42:45], v[208:211], v[152:155], v[42:45]
	v_mfma_f32_16x16x32_bf16 v[34:37], v[212:215], v[152:155], v[34:37]
	v_mfma_f32_16x16x32_bf16 v[30:33], v[188:191], v[156:159], v[30:33]
	v_mfma_f32_16x16x32_bf16 v[22:25], v[192:195], v[156:159], v[22:25]
	v_mfma_f32_16x16x32_bf16 v[26:29], v[208:211], v[156:159], v[26:29]
	v_mfma_f32_16x16x32_bf16 v[18:21], v[212:215], v[156:159], v[18:21]
	v_mfma_f32_16x16x32_bf16 v[14:17], v[188:191], v[160:163], v[14:17]
	v_mfma_f32_16x16x32_bf16 v[6:9], v[192:195], v[160:163], v[6:9]
	v_mfma_f32_16x16x32_bf16 v[10:13], v[208:211], v[160:163], v[10:13]
	v_mfma_f32_16x16x32_bf16 v[2:5], v[212:215], v[160:163], v[2:5]
	v_mfma_f32_16x16x32_bf16 v[66:69], v[188:191], v[164:167], v[66:69]
	v_mfma_f32_16x16x32_bf16 v[70:73], v[192:195], v[164:167], v[70:73]
	v_mfma_f32_16x16x32_bf16 v[82:85], v[208:211], v[164:167], v[82:85]
	v_mfma_f32_16x16x32_bf16 v[86:89], v[212:215], v[164:167], v[86:89]
	v_mfma_f32_16x16x32_bf16 v[90:93], v[188:191], v[168:171], v[90:93]
	v_mfma_f32_16x16x32_bf16 v[94:97], v[192:195], v[168:171], v[94:97]
	v_mfma_f32_16x16x32_bf16 v[98:101], v[208:211], v[168:171], v[98:101]
	v_mfma_f32_16x16x32_bf16 v[102:105], v[212:215], v[168:171], v[102:105]
	v_mfma_f32_16x16x32_bf16 v[106:109], v[188:191], v[174:177], v[106:109]
	v_mfma_f32_16x16x32_bf16 v[110:113], v[192:195], v[174:177], v[110:113]
	v_mfma_f32_16x16x32_bf16 v[114:117], v[208:211], v[174:177], v[114:117]
	v_mfma_f32_16x16x32_bf16 v[118:121], v[212:215], v[174:177], v[118:121]
	v_mfma_f32_16x16x32_bf16 v[122:125], v[188:191], v[182:185], v[122:125]
	v_mfma_f32_16x16x32_bf16 v[126:129], v[192:195], v[182:185], v[126:129]
	v_mfma_f32_16x16x32_bf16 v[136:139], v[208:211], v[182:185], v[136:139]
	v_mfma_f32_16x16x32_bf16 v[140:143], v[212:215], v[182:185], v[140:143]
	s_waitcnt vmcnt(0)
	s_barrier
	ds_read_b128 v[148:151], v80 offset:0
	ds_read_b128 v[152:155], v80 offset:2048
	ds_read_b128 v[156:159], v80 offset:4096
	ds_read_b128 v[160:163], v80 offset:6144
	ds_read_b128 v[188:191], v144 offset:49152
	ds_read_b128 v[192:195], v144 offset:51200
	ds_read_b128 v[208:211], v144 offset:53248
	ds_read_b128 v[212:215], v144 offset:55296
	ds_read_b128 v[164:167], v80 offset:16384
	ds_read_b128 v[168:171], v80 offset:18432
	ds_read_b128 v[174:177], v80 offset:20480
	ds_read_b128 v[182:185], v80 offset:22528
	s_waitcnt lgkmcnt(4)
	v_mfma_f32_16x16x32_bf16 v[62:65], v[188:191], v[148:151], v[62:65]
	v_mfma_f32_16x16x32_bf16 v[54:57], v[192:195], v[148:151], v[54:57]
	v_mfma_f32_16x16x32_bf16 v[58:61], v[208:211], v[148:151], v[58:61]
	v_mfma_f32_16x16x32_bf16 v[50:53], v[212:215], v[148:151], v[50:53]
	v_mfma_f32_16x16x32_bf16 v[46:49], v[188:191], v[152:155], v[46:49]
	v_mfma_f32_16x16x32_bf16 v[38:41], v[192:195], v[152:155], v[38:41]
	v_mfma_f32_16x16x32_bf16 v[42:45], v[208:211], v[152:155], v[42:45]
	v_mfma_f32_16x16x32_bf16 v[34:37], v[212:215], v[152:155], v[34:37]
	v_mfma_f32_16x16x32_bf16 v[30:33], v[188:191], v[156:159], v[30:33]
	v_mfma_f32_16x16x32_bf16 v[22:25], v[192:195], v[156:159], v[22:25]
	v_mfma_f32_16x16x32_bf16 v[26:29], v[208:211], v[156:159], v[26:29]
	v_mfma_f32_16x16x32_bf16 v[18:21], v[212:215], v[156:159], v[18:21]
	v_mfma_f32_16x16x32_bf16 v[14:17], v[188:191], v[160:163], v[14:17]
	v_mfma_f32_16x16x32_bf16 v[6:9], v[192:195], v[160:163], v[6:9]
	v_mfma_f32_16x16x32_bf16 v[10:13], v[208:211], v[160:163], v[10:13]
	v_mfma_f32_16x16x32_bf16 v[2:5], v[212:215], v[160:163], v[2:5]
	s_waitcnt lgkmcnt(0)
	v_mfma_f32_16x16x32_bf16 v[66:69], v[188:191], v[164:167], v[66:69]
	v_mfma_f32_16x16x32_bf16 v[70:73], v[192:195], v[164:167], v[70:73]
	v_mfma_f32_16x16x32_bf16 v[82:85], v[208:211], v[164:167], v[82:85]
	v_mfma_f32_16x16x32_bf16 v[86:89], v[212:215], v[164:167], v[86:89]
	v_mfma_f32_16x16x32_bf16 v[90:93], v[188:191], v[168:171], v[90:93]
	v_mfma_f32_16x16x32_bf16 v[94:97], v[192:195], v[168:171], v[94:97]
	v_mfma_f32_16x16x32_bf16 v[98:101], v[208:211], v[168:171], v[98:101]
	v_mfma_f32_16x16x32_bf16 v[102:105], v[212:215], v[168:171], v[102:105]
	v_mfma_f32_16x16x32_bf16 v[106:109], v[188:191], v[174:177], v[106:109]
	v_mfma_f32_16x16x32_bf16 v[110:113], v[192:195], v[174:177], v[110:113]
	v_mfma_f32_16x16x32_bf16 v[114:117], v[208:211], v[174:177], v[114:117]
	v_mfma_f32_16x16x32_bf16 v[118:121], v[212:215], v[174:177], v[118:121]
	v_mfma_f32_16x16x32_bf16 v[122:125], v[188:191], v[182:185], v[122:125]
	v_mfma_f32_16x16x32_bf16 v[126:129], v[192:195], v[182:185], v[126:129]
	v_mfma_f32_16x16x32_bf16 v[136:139], v[208:211], v[182:185], v[136:139]
	v_mfma_f32_16x16x32_bf16 v[140:143], v[212:215], v[182:185], v[140:143]
	ds_read_b128 v[148:151], v81 offset:0
	ds_read_b128 v[152:155], v81 offset:2048
	ds_read_b128 v[156:159], v81 offset:4096
	ds_read_b128 v[160:163], v81 offset:6144
	ds_read_b128 v[188:191], v145 offset:49152
	ds_read_b128 v[192:195], v145 offset:51200
	ds_read_b128 v[208:211], v145 offset:53248
	ds_read_b128 v[212:215], v145 offset:55296
	ds_read_b128 v[164:167], v81 offset:16384
	ds_read_b128 v[168:171], v81 offset:18432
	ds_read_b128 v[174:177], v81 offset:20480
	ds_read_b128 v[182:185], v81 offset:22528
	s_waitcnt lgkmcnt(4)
	v_mfma_f32_16x16x32_bf16 v[62:65], v[188:191], v[148:151], v[62:65]
	v_mfma_f32_16x16x32_bf16 v[54:57], v[192:195], v[148:151], v[54:57]
	v_mfma_f32_16x16x32_bf16 v[58:61], v[208:211], v[148:151], v[58:61]
	v_mfma_f32_16x16x32_bf16 v[50:53], v[212:215], v[148:151], v[50:53]
	v_mfma_f32_16x16x32_bf16 v[46:49], v[188:191], v[152:155], v[46:49]
	v_mfma_f32_16x16x32_bf16 v[38:41], v[192:195], v[152:155], v[38:41]
	v_mfma_f32_16x16x32_bf16 v[42:45], v[208:211], v[152:155], v[42:45]
	v_mfma_f32_16x16x32_bf16 v[34:37], v[212:215], v[152:155], v[34:37]
	v_mfma_f32_16x16x32_bf16 v[30:33], v[188:191], v[156:159], v[30:33]
	v_mfma_f32_16x16x32_bf16 v[22:25], v[192:195], v[156:159], v[22:25]
	v_mfma_f32_16x16x32_bf16 v[26:29], v[208:211], v[156:159], v[26:29]
	v_mfma_f32_16x16x32_bf16 v[18:21], v[212:215], v[156:159], v[18:21]
	v_mfma_f32_16x16x32_bf16 v[14:17], v[188:191], v[160:163], v[14:17]
	v_mfma_f32_16x16x32_bf16 v[6:9], v[192:195], v[160:163], v[6:9]
	v_mfma_f32_16x16x32_bf16 v[10:13], v[208:211], v[160:163], v[10:13]
	v_mfma_f32_16x16x32_bf16 v[2:5], v[212:215], v[160:163], v[2:5]
	s_waitcnt lgkmcnt(0)
	v_mfma_f32_16x16x32_bf16 v[66:69], v[188:191], v[164:167], v[66:69]
	v_mfma_f32_16x16x32_bf16 v[70:73], v[192:195], v[164:167], v[70:73]
	v_mfma_f32_16x16x32_bf16 v[82:85], v[208:211], v[164:167], v[82:85]
	v_mfma_f32_16x16x32_bf16 v[86:89], v[212:215], v[164:167], v[86:89]
	v_mfma_f32_16x16x32_bf16 v[90:93], v[188:191], v[168:171], v[90:93]
	v_mfma_f32_16x16x32_bf16 v[94:97], v[192:195], v[168:171], v[94:97]
	v_mfma_f32_16x16x32_bf16 v[98:101], v[208:211], v[168:171], v[98:101]
	v_mfma_f32_16x16x32_bf16 v[102:105], v[212:215], v[168:171], v[102:105]
	v_mfma_f32_16x16x32_bf16 v[106:109], v[188:191], v[174:177], v[106:109]
	v_mfma_f32_16x16x32_bf16 v[110:113], v[192:195], v[174:177], v[110:113]
	v_mfma_f32_16x16x32_bf16 v[114:117], v[208:211], v[174:177], v[114:117]
	v_mfma_f32_16x16x32_bf16 v[118:121], v[212:215], v[174:177], v[118:121]
	v_mfma_f32_16x16x32_bf16 v[122:125], v[188:191], v[182:185], v[122:125]
	v_mfma_f32_16x16x32_bf16 v[126:129], v[192:195], v[182:185], v[126:129]
	v_mfma_f32_16x16x32_bf16 v[136:139], v[208:211], v[182:185], v[136:139]
	v_mfma_f32_16x16x32_bf16 v[140:143], v[212:215], v[182:185], v[140:143]
	s_nop 7
	s_nop 7
	s_nop 7
	s_add_i32 s48, s48, 1
	s_mov_b32 s39, 0
	v_readlane_b32 s30, v249, 0
	s_nop 0
	s_and_b32 s31, s30, 7
	s_lshr_b32 s30, s30, 3
	s_cmp_lt_u32 s30, 32
	s_cselect_b32 s35, 6, 5
	s_cmp_lt_u32 s48, s35
	s_cbranch_scc0 .Lf2_c1_extra
	s_lshl_b32 s33, s48, 6
	s_add_i32 s33, s33, s30
	s_cmp_ge_u32 s33, 0xb0
	s_cselect_b32 s34, 1, 0
	s_mul_i32 s36, s34, 0xb0
	s_sub_i32 s33, s33, s36
	s_lshr_b32 s37, s33, 2
	s_and_b32 s33, s33, 3
	s_lshl_b32 s34, s34, 3
	s_add_i32 s33, s33, s34
	s_lshl_b32 s33, s33, 3
	s_add_i32 s36, s33, s31
	s_add_i32 s38, s36, 32
	s_branch .Lf2_c1_have

.Lr2o_k:
	s_waitcnt vmcnt(0)
	s_barrier
	s_add_i32 m0, s36, 0xc000
	s_nop 0
	global_load_lds_dwordx4 v136, s[34:35]
	s_add_i32 m0, s36, 0xd000
	s_nop 0
	global_load_lds_dwordx4 v137, s[34:35]
	s_add_i32 m0, s36, 0xe000
	s_nop 0
	global_load_lds_dwordx4 v138, s[34:35]
	s_add_i32 m0, s36, 0xf000
	s_nop 0
	global_load_lds_dwordx4 v139, s[34:35]
	s_add_u32 s34, s34, 0x80
	s_addc_u32 s35, s35, 0
	ds_read_b128 v[148:151], v140 offset:0
	ds_read_b128 v[152:155], v140 offset:2048
	ds_read_b128 v[156:159], v140 offset:4096
	ds_read_b128 v[160:163], v140 offset:6144
	ds_read_b128 v[164:167], v140 offset:16384
	ds_read_b128 v[168:171], v140 offset:18432
	ds_read_b128 v[174:177], v140 offset:20480
	ds_read_b128 v[182:185], v140 offset:22528
	ds_read_b128 v[188:191], v142 offset:32768
	ds_read_b128 v[192:195], v142 offset:34816
	ds_read_b128 v[208:211], v142 offset:36864
	ds_read_b128 v[212:215], v142 offset:38912
	s_waitcnt lgkmcnt(0)
	v_mfma_f32_16x16x32_bf16 v[62:65], v[188:191], v[148:151], v[62:65]
	v_mfma_f32_16x16x32_bf16 v[58:61], v[192:195], v[148:151], v[58:61]
	v_mfma_f32_16x16x32_bf16 v[54:57], v[208:211], v[148:151], v[54:57]
	v_mfma_f32_16x16x32_bf16 v[50:53], v[212:215], v[148:151], v[50:53]
	v_mfma_f32_16x16x32_bf16 v[46:49], v[188:191], v[152:155], v[46:49]
	v_mfma_f32_16x16x32_bf16 v[42:45], v[192:195], v[152:155], v[42:45]
	v_mfma_f32_16x16x32_bf16 v[38:41], v[208:211], v[152:155], v[38:41]
	v_mfma_f32_16x16x32_bf16 v[34:37], v[212:215], v[152:155], v[34:37]
	v_mfma_f32_16x16x32_bf16 v[30:33], v[188:191], v[156:159], v[30:33]
	v_mfma_f32_16x16x32_bf16 v[26:29], v[192:195], v[156:159], v[26:29]
	v_mfma_f32_16x16x32_bf16 v[22:25], v[208:211], v[156:159], v[22:25]
	v_mfma_f32_16x16x32_bf16 v[18:21], v[212:215], v[156:159], v[18:21]
	v_mfma_f32_16x16x32_bf16 v[14:17], v[188:191], v[160:163], v[14:17]
	v_mfma_f32_16x16x32_bf16 v[10:13], v[192:195], v[160:163], v[10:13]
	v_mfma_f32_16x16x32_bf16 v[6:9], v[208:211], v[160:163], v[6:9]
	v_mfma_f32_16x16x32_bf16 v[2:5], v[212:215], v[160:163], v[2:5]
	v_mfma_f32_16x16x32_bf16 v[66:69], v[188:191], v[164:167], v[66:69]
	v_mfma_f32_16x16x32_bf16 v[70:73], v[192:195], v[164:167], v[70:73]
	v_mfma_f32_16x16x32_bf16 v[74:77], v[208:211], v[164:167], v[74:77]
	v_mfma_f32_16x16x32_bf16 v[78:81], v[212:215], v[164:167], v[78:81]
	v_mfma_f32_16x16x32_bf16 v[82:85], v[188:191], v[168:171], v[82:85]
	v_mfma_f32_16x16x32_bf16 v[86:89], v[192:195], v[168:171], v[86:89]
	v_mfma_f32_16x16x32_bf16 v[90:93], v[208:211], v[168:171], v[90:93]
	v_mfma_f32_16x16x32_bf16 v[94:97], v[212:215], v[168:171], v[94:97]
	v_mfma_f32_16x16x32_bf16 v[98:101], v[188:191], v[174:177], v[98:101]
	v_mfma_f32_16x16x32_bf16 v[102:105], v[192:195], v[174:177], v[102:105]
	v_mfma_f32_16x16x32_bf16 v[106:109], v[208:211], v[174:177], v[106:109]
	v_mfma_f32_16x16x32_bf16 v[110:113], v[212:215], v[174:177], v[110:113]
	v_mfma_f32_16x16x32_bf16 v[114:117], v[188:191], v[182:185], v[114:117]
	v_mfma_f32_16x16x32_bf16 v[118:121], v[192:195], v[182:185], v[118:121]
	v_mfma_f32_16x16x32_bf16 v[122:125], v[208:211], v[182:185], v[122:125]
	v_mfma_f32_16x16x32_bf16 v[126:129], v[212:215], v[182:185], v[126:129]
	ds_read_b128 v[148:151], v141 offset:0
	ds_read_b128 v[152:155], v141 offset:2048
	ds_read_b128 v[156:159], v141 offset:4096
	ds_read_b128 v[160:163], v141 offset:6144
	ds_read_b128 v[164:167], v141 offset:16384
	ds_read_b128 v[168:171], v141 offset:18432
	ds_read_b128 v[174:177], v141 offset:20480
	ds_read_b128 v[182:185], v141 offset:22528
	ds_read_b128 v[188:191], v143 offset:32768
	ds_read_b128 v[192:195], v143 offset:34816
	ds_read_b128 v[208:211], v143 offset:36864
	ds_read_b128 v[212:215], v143 offset:38912
	s_waitcnt lgkmcnt(0)
	s_barrier
	s_add_i32 m0, s36, 0x0
	s_nop 0
	global_load_lds_dwordx4 v136, s[30:31]
	s_add_i32 m0, s36, 0x1000
	s_nop 0
	global_load_lds_dwordx4 v137, s[30:31]
	s_add_i32 m0, s36, 0x2000
	s_nop 0
	global_load_lds_dwordx4 v138, s[30:31]
	s_add_i32 m0, s36, 0x3000
	s_nop 0
	global_load_lds_dwordx4 v139, s[30:31]
	s_add_i32 m0, s36, 0x4000
	s_nop 0
	global_load_lds_dwordx4 v136, s[44:45]
	s_add_i32 m0, s36, 0x5000
	s_nop 0
	global_load_lds_dwordx4 v137, s[44:45]
	s_add_i32 m0, s36, 0x6000
	s_nop 0
	global_load_lds_dwordx4 v138, s[44:45]
	s_add_i32 m0, s36, 0x7000
	s_nop 0
	global_load_lds_dwordx4 v139, s[44:45]
	s_add_u32 s30, s30, 0x80
	s_addc_u32 s31, s31, 0
	s_add_u32 s44, s44, 0x80
	s_addc_u32 s45, s45, 0
	v_mfma_f32_16x16x32_bf16 v[62:65], v[188:191], v[148:151], v[62:65]
	v_mfma_f32_16x16x32_bf16 v[58:61], v[192:195], v[148:151], v[58:61]
	v_mfma_f32_16x16x32_bf16 v[54:57], v[208:211], v[148:151], v[54:57]
	v_mfma_f32_16x16x32_bf16 v[50:53], v[212:215], v[148:151], v[50:53]
	v_mfma_f32_16x16x32_bf16 v[46:49], v[188:191], v[152:155], v[46:49]
	v_mfma_f32_16x16x32_bf16 v[42:45], v[192:195], v[152:155], v[42:45]
	v_mfma_f32_16x16x32_bf16 v[38:41], v[208:211], v[152:155], v[38:41]
	v_mfma_f32_16x16x32_bf16 v[34:37], v[212:215], v[152:155], v[34:37]
	v_mfma_f32_16x16x32_bf16 v[30:33], v[188:191], v[156:159], v[30:33]
	v_mfma_f32_16x16x32_bf16 v[26:29], v[192:195], v[156:159], v[26:29]
	v_mfma_f32_16x16x32_bf16 v[22:25], v[208:211], v[156:159], v[22:25]
	v_mfma_f32_16x16x32_bf16 v[18:21], v[212:215], v[156:159], v[18:21]
	v_mfma_f32_16x16x32_bf16 v[14:17], v[188:191], v[160:163], v[14:17]
	v_mfma_f32_16x16x32_bf16 v[10:13], v[192:195], v[160:163], v[10:13]
	v_mfma_f32_16x16x32_bf16 v[6:9], v[208:211], v[160:163], v[6:9]
	v_mfma_f32_16x16x32_bf16 v[2:5], v[212:215], v[160:163], v[2:5]
	v_mfma_f32_16x16x32_bf16 v[66:69], v[188:191], v[164:167], v[66:69]
	v_mfma_f32_16x16x32_bf16 v[70:73], v[192:195], v[164:167], v[70:73]
	v_mfma_f32_16x16x32_bf16 v[74:77], v[208:211], v[164:167], v[74:77]
	v_mfma_f32_16x16x32_bf16 v[78:81], v[212:215], v[164:167], v[78:81]
	v_mfma_f32_16x16x32_bf16 v[82:85], v[188:191], v[168:171], v[82:85]
	v_mfma_f32_16x16x32_bf16 v[86:89], v[192:195], v[168:171], v[86:89]
	v_mfma_f32_16x16x32_bf16 v[90:93], v[208:211], v[168:171], v[90:93]
	v_mfma_f32_16x16x32_bf16 v[94:97], v[212:215], v[168:171], v[94:97]
	v_mfma_f32_16x16x32_bf16 v[98:101], v[188:191], v[174:177], v[98:101]
	v_mfma_f32_16x16x32_bf16 v[102:105], v[192:195], v[174:177], v[102:105]
	v_mfma_f32_16x16x32_bf16 v[106:109], v[208:211], v[174:177], v[106:109]
	v_mfma_f32_16x16x32_bf16 v[110:113], v[212:215], v[174:177], v[110:113]
	v_mfma_f32_16x16x32_bf16 v[114:117], v[188:191], v[182:185], v[114:117]
	v_mfma_f32_16x16x32_bf16 v[118:121], v[192:195], v[182:185], v[118:121]
	v_mfma_f32_16x16x32_bf16 v[122:125], v[208:211], v[182:185], v[122:125]
	v_mfma_f32_16x16x32_bf16 v[126:129], v[212:215], v[182:185], v[126:129]
	s_waitcnt vmcnt(0)
	s_barrier
	s_add_i32 m0, s36, 0x8000
	s_nop 0
	global_load_lds_dwordx4 v136, s[34:35]
	s_add_i32 m0, s36, 0x9000
	s_nop 0
	global_load_lds_dwordx4 v137, s[34:35]
	s_add_i32 m0, s36, 0xa000
	s_nop 0
	global_load_lds_dwordx4 v138, s[34:35]
	s_add_i32 m0, s36, 0xb000
	s_nop 0
	global_load_lds_dwordx4 v139, s[34:35]
	s_add_u32 s34, s34, 0x80
	s_addc_u32 s35, s35, 0
	ds_read_b128 v[148:151], v140 offset:0
	ds_read_b128 v[152:155], v140 offset:2048
	ds_read_b128 v[156:159], v140 offset:4096
	ds_read_b128 v[160:163], v140 offset:6144
	ds_read_b128 v[164:167], v140 offset:16384
	ds_read_b128 v[168:171], v140 offset:18432
	ds_read_b128 v[174:177], v140 offset:20480
	ds_read_b128 v[182:185], v140 offset:22528
	ds_read_b128 v[188:191], v142 offset:49152
	ds_read_b128 v[192:195], v142 offset:51200
	ds_read_b128 v[208:211], v142 offset:53248
	ds_read_b128 v[212:215], v142 offset:55296
	s_waitcnt lgkmcnt(0)
	v_mfma_f32_16x16x32_bf16 v[62:65], v[188:191], v[148:151], v[62:65]
	v_mfma_f32_16x16x32_bf16 v[58:61], v[192:195], v[148:151], v[58:61]
	v_mfma_f32_16x16x32_bf16 v[54:57], v[208:211], v[148:151], v[54:57]
	v_mfma_f32_16x16x32_bf16 v[50:53], v[212:215], v[148:151], v[50:53]
	v_mfma_f32_16x16x32_bf16 v[46:49], v[188:191], v[152:155], v[46:49]
	v_mfma_f32_16x16x32_bf16 v[42:45], v[192:195], v[152:155], v[42:45]
	v_mfma_f32_16x16x32_bf16 v[38:41], v[208:211], v[152:155], v[38:41]
	v_mfma_f32_16x16x32_bf16 v[34:37], v[212:215], v[152:155], v[34:37]
	v_mfma_f32_16x16x32_bf16 v[30:33], v[188:191], v[156:159], v[30:33]
	v_mfma_f32_16x16x32_bf16 v[26:29], v[192:195], v[156:159], v[26:29]
	v_mfma_f32_16x16x32_bf16 v[22:25], v[208:211], v[156:159], v[22:25]
	v_mfma_f32_16x16x32_bf16 v[18:21], v[212:215], v[156:159], v[18:21]
	v_mfma_f32_16x16x32_bf16 v[14:17], v[188:191], v[160:163], v[14:17]
	v_mfma_f32_16x16x32_bf16 v[10:13], v[192:195], v[160:163], v[10:13]
	v_mfma_f32_16x16x32_bf16 v[6:9], v[208:211], v[160:163], v[6:9]
	v_mfma_f32_16x16x32_bf16 v[2:5], v[212:215], v[160:163], v[2:5]
	v_mfma_f32_16x16x32_bf16 v[66:69], v[188:191], v[164:167], v[66:69]
	v_mfma_f32_16x16x32_bf16 v[70:73], v[192:195], v[164:167], v[70:73]
	v_mfma_f32_16x16x32_bf16 v[74:77], v[208:211], v[164:167], v[74:77]
	v_mfma_f32_16x16x32_bf16 v[78:81], v[212:215], v[164:167], v[78:81]
	v_mfma_f32_16x16x32_bf16 v[82:85], v[188:191], v[168:171], v[82:85]
	v_mfma_f32_16x16x32_bf16 v[86:89], v[192:195], v[168:171], v[86:89]
	v_mfma_f32_16x16x32_bf16 v[90:93], v[208:211], v[168:171], v[90:93]
	v_mfma_f32_16x16x32_bf16 v[94:97], v[212:215], v[168:171], v[94:97]
	v_mfma_f32_16x16x32_bf16 v[98:101], v[188:191], v[174:177], v[98:101]
	v_mfma_f32_16x16x32_bf16 v[102:105], v[192:195], v[174:177], v[102:105]
	v_mfma_f32_16x16x32_bf16 v[106:109], v[208:211], v[174:177], v[106:109]
	v_mfma_f32_16x16x32_bf16 v[110:113], v[212:215], v[174:177], v[110:113]
	v_mfma_f32_16x16x32_bf16 v[114:117], v[188:191], v[182:185], v[114:117]
	v_mfma_f32_16x16x32_bf16 v[118:121], v[192:195], v[182:185], v[118:121]
	v_mfma_f32_16x16x32_bf16 v[122:125], v[208:211], v[182:185], v[122:125]
	v_mfma_f32_16x16x32_bf16 v[126:129], v[212:215], v[182:185], v[126:129]
	ds_read_b128 v[148:151], v141 offset:0
	ds_read_b128 v[152:155], v141 offset:2048
	ds_read_b128 v[156:159], v141 offset:4096
	ds_read_b128 v[160:163], v141 offset:6144
	ds_read_b128 v[164:167], v141 offset:16384
	ds_read_b128 v[168:171], v141 offset:18432
	ds_read_b128 v[174:177], v141 offset:20480
	ds_read_b128 v[182:185], v141 offset:22528
	ds_read_b128 v[188:191], v143 offset:49152
	ds_read_b128 v[192:195], v143 offset:51200
	ds_read_b128 v[208:211], v143 offset:53248
	ds_read_b128 v[212:215], v143 offset:55296
	s_waitcnt lgkmcnt(0)
	s_barrier
	s_add_i32 m0, s36, 0x0
	s_nop 0
	global_load_lds_dwordx4 v136, s[30:31]
	s_add_i32 m0, s36, 0x1000
	s_nop 0
	global_load_lds_dwordx4 v137, s[30:31]
	s_add_i32 m0, s36, 0x2000
	s_nop 0
	global_load_lds_dwordx4 v138, s[30:31]
	s_add_i32 m0, s36, 0x3000
	s_nop 0
	global_load_lds_dwordx4 v139, s[30:31]
	s_add_i32 m0, s36, 0x4000
	s_nop 0
	global_load_lds_dwordx4 v136, s[44:45]
	s_add_i32 m0, s36, 0x5000
	s_nop 0
	global_load_lds_dwordx4 v137, s[44:45]
	s_add_i32 m0, s36, 0x6000
	s_nop 0
	global_load_lds_dwordx4 v138, s[44:45]
	s_add_i32 m0, s36, 0x7000
	s_nop 0
	global_load_lds_dwordx4 v139, s[44:45]
	s_add_u32 s30, s30, 0x80
	s_addc_u32 s31, s31, 0
	s_add_u32 s44, s44, 0x80
	s_addc_u32 s45, s45, 0
	v_mfma_f32_16x16x32_bf16 v[62:65], v[188:191], v[148:151], v[62:65]
	v_mfma_f32_16x16x32_bf16 v[58:61], v[192:195], v[148:151], v[58:61]
	v_mfma_f32_16x16x32_bf16 v[54:57], v[208:211], v[148:151], v[54:57]
	v_mfma_f32_16x16x32_bf16 v[50:53], v[212:215], v[148:151], v[50:53]
	v_mfma_f32_16x16x32_bf16 v[46:49], v[188:191], v[152:155], v[46:49]
	v_mfma_f32_16x16x32_bf16 v[42:45], v[192:195], v[152:155], v[42:45]
	v_mfma_f32_16x16x32_bf16 v[38:41], v[208:211], v[152:155], v[38:41]
	v_mfma_f32_16x16x32_bf16 v[34:37], v[212:215], v[152:155], v[34:37]
	v_mfma_f32_16x16x32_bf16 v[30:33], v[188:191], v[156:159], v[30:33]
	v_mfma_f32_16x16x32_bf16 v[26:29], v[192:195], v[156:159], v[26:29]
	v_mfma_f32_16x16x32_bf16 v[22:25], v[208:211], v[156:159], v[22:25]
	v_mfma_f32_16x16x32_bf16 v[18:21], v[212:215], v[156:159], v[18:21]
	v_mfma_f32_16x16x32_bf16 v[14:17], v[188:191], v[160:163], v[14:17]
	v_mfma_f32_16x16x32_bf16 v[10:13], v[192:195], v[160:163], v[10:13]
	v_mfma_f32_16x16x32_bf16 v[6:9], v[208:211], v[160:163], v[6:9]
	v_mfma_f32_16x16x32_bf16 v[2:5], v[212:215], v[160:163], v[2:5]
	v_mfma_f32_16x16x32_bf16 v[66:69], v[188:191], v[164:167], v[66:69]
	v_mfma_f32_16x16x32_bf16 v[70:73], v[192:195], v[164:167], v[70:73]
	v_mfma_f32_16x16x32_bf16 v[74:77], v[208:211], v[164:167], v[74:77]
	v_mfma_f32_16x16x32_bf16 v[78:81], v[212:215], v[164:167], v[78:81]
	v_mfma_f32_16x16x32_bf16 v[82:85], v[188:191], v[168:171], v[82:85]
	v_mfma_f32_16x16x32_bf16 v[86:89], v[192:195], v[168:171], v[86:89]
	v_mfma_f32_16x16x32_bf16 v[90:93], v[208:211], v[168:171], v[90:93]
	v_mfma_f32_16x16x32_bf16 v[94:97], v[212:215], v[168:171], v[94:97]
	v_mfma_f32_16x16x32_bf16 v[98:101], v[188:191], v[174:177], v[98:101]
	v_mfma_f32_16x16x32_bf16 v[102:105], v[192:195], v[174:177], v[102:105]
	v_mfma_f32_16x16x32_bf16 v[106:109], v[208:211], v[174:177], v[106:109]
	v_mfma_f32_16x16x32_bf16 v[110:113], v[212:215], v[174:177], v[110:113]
	v_mfma_f32_16x16x32_bf16 v[114:117], v[188:191], v[182:185], v[114:117]
	v_mfma_f32_16x16x32_bf16 v[118:121], v[192:195], v[182:185], v[118:121]
	v_mfma_f32_16x16x32_bf16 v[122:125], v[208:211], v[182:185], v[122:125]
	v_mfma_f32_16x16x32_bf16 v[126:129], v[212:215], v[182:185], v[126:129]
	s_add_i32 s37, s37, -1
	s_cmp_lg_u32 s37, 0
	s_cbranch_scc1 .Lr2o_k
	s_waitcnt vmcnt(0)
	s_barrier
	s_add_i32 m0, s36, 0xc000
	s_nop 0
	global_load_lds_dwordx4 v136, s[34:35]
	s_add_i32 m0, s36, 0xd000
	s_nop 0
	global_load_lds_dwordx4 v137, s[34:35]
	s_add_i32 m0, s36, 0xe000
	s_nop 0
	global_load_lds_dwordx4 v138, s[34:35]
	s_add_i32 m0, s36, 0xf000
	s_nop 0
	global_load_lds_dwordx4 v139, s[34:35]
	s_add_u32 s34, s34, 0x80
	s_addc_u32 s35, s35, 0
	ds_read_b128 v[148:151], v140 offset:0
	ds_read_b128 v[152:155], v140 offset:2048
	ds_read_b128 v[156:159], v140 offset:4096
	ds_read_b128 v[160:163], v140 offset:6144
	ds_read_b128 v[164:167], v140 offset:16384
	ds_read_b128 v[168:171], v140 offset:18432
	ds_read_b128 v[174:177], v140 offset:20480
	ds_read_b128 v[182:185], v140 offset:22528
	ds_read_b128 v[188:191], v142 offset:32768
	ds_read_b128 v[192:195], v142 offset:34816
	ds_read_b128 v[208:211], v142 offset:36864
	ds_read_b128 v[212:215], v142 offset:38912
	s_waitcnt lgkmcnt(0)
	v_mfma_f32_16x16x32_bf16 v[62:65], v[188:191], v[148:151], v[62:65]
	v_mfma_f32_16x16x32_bf16 v[58:61], v[192:195], v[148:151], v[58:61]
	v_mfma_f32_16x16x32_bf16 v[54:57], v[208:211], v[148:151], v[54:57]
	v_mfma_f32_16x16x32_bf16 v[50:53], v[212:215], v[148:151], v[50:53]
	v_mfma_f32_16x16x32_bf16 v[46:49], v[188:191], v[152:155], v[46:49]
	v_mfma_f32_16x16x32_bf16 v[42:45], v[192:195], v[152:155], v[42:45]
	v_mfma_f32_16x16x32_bf16 v[38:41], v[208:211], v[152:155], v[38:41]
	v_mfma_f32_16x16x32_bf16 v[34:37], v[212:215], v[152:155], v[34:37]
	v_mfma_f32_16x16x32_bf16 v[30:33], v[188:191], v[156:159], v[30:33]
	v_mfma_f32_16x16x32_bf16 v[26:29], v[192:195], v[156:159], v[26:29]
	v_mfma_f32_16x16x32_bf16 v[22:25], v[208:211], v[156:159], v[22:25]
	v_mfma_f32_16x16x32_bf16 v[18:21], v[212:215], v[156:159], v[18:21]
	v_mfma_f32_16x16x32_bf16 v[14:17], v[188:191], v[160:163], v[14:17]
	v_mfma_f32_16x16x32_bf16 v[10:13], v[192:195], v[160:163], v[10:13]
	v_mfma_f32_16x16x32_bf16 v[6:9], v[208:211], v[160:163], v[6:9]
	v_mfma_f32_16x16x32_bf16 v[2:5], v[212:215], v[160:163], v[2:5]
	v_mfma_f32_16x16x32_bf16 v[66:69], v[188:191], v[164:167], v[66:69]
	v_mfma_f32_16x16x32_bf16 v[70:73], v[192:195], v[164:167], v[70:73]
	v_mfma_f32_16x16x32_bf16 v[74:77], v[208:211], v[164:167], v[74:77]
	v_mfma_f32_16x16x32_bf16 v[78:81], v[212:215], v[164:167], v[78:81]
	v_mfma_f32_16x16x32_bf16 v[82:85], v[188:191], v[168:171], v[82:85]
	v_mfma_f32_16x16x32_bf16 v[86:89], v[192:195], v[168:171], v[86:89]
	v_mfma_f32_16x16x32_bf16 v[90:93], v[208:211], v[168:171], v[90:93]
	v_mfma_f32_16x16x32_bf16 v[94:97], v[212:215], v[168:171], v[94:97]
	v_mfma_f32_16x16x32_bf16 v[98:101], v[188:191], v[174:177], v[98:101]
	v_mfma_f32_16x16x32_bf16 v[102:105], v[192:195], v[174:177], v[102:105]
	v_mfma_f32_16x16x32_bf16 v[106:109], v[208:211], v[174:177], v[106:109]
	v_mfma_f32_16x16x32_bf16 v[110:113], v[212:215], v[174:177], v[110:113]
	v_mfma_f32_16x16x32_bf16 v[114:117], v[188:191], v[182:185], v[114:117]
	v_mfma_f32_16x16x32_bf16 v[118:121], v[192:195], v[182:185], v[118:121]
	v_mfma_f32_16x16x32_bf16 v[122:125], v[208:211], v[182:185], v[122:125]
	v_mfma_f32_16x16x32_bf16 v[126:129], v[212:215], v[182:185], v[126:129]
	ds_read_b128 v[148:151], v141 offset:0
	ds_read_b128 v[152:155], v141 offset:2048
	ds_read_b128 v[156:159], v141 offset:4096
	ds_read_b128 v[160:163], v141 offset:6144
	ds_read_b128 v[164:167], v141 offset:16384
	ds_read_b128 v[168:171], v141 offset:18432
	ds_read_b128 v[174:177], v141 offset:20480
	ds_read_b128 v[182:185], v141 offset:22528
	ds_read_b128 v[188:191], v143 offset:32768
	ds_read_b128 v[192:195], v143 offset:34816
	ds_read_b128 v[208:211], v143 offset:36864
	ds_read_b128 v[212:215], v143 offset:38912
	s_waitcnt lgkmcnt(0)
	s_barrier
	s_add_i32 m0, s36, 0x0
	s_nop 0
	global_load_lds_dwordx4 v136, s[30:31]
	s_add_i32 m0, s36, 0x1000
	s_nop 0
	global_load_lds_dwordx4 v137, s[30:31]
	s_add_i32 m0, s36, 0x2000
	s_nop 0
	global_load_lds_dwordx4 v138, s[30:31]
	s_add_i32 m0, s36, 0x3000
	s_nop 0
	global_load_lds_dwordx4 v139, s[30:31]
	s_add_i32 m0, s36, 0x4000
	s_nop 0
	global_load_lds_dwordx4 v136, s[44:45]
	s_add_i32 m0, s36, 0x5000
	s_nop 0
	global_load_lds_dwordx4 v137, s[44:45]
	s_add_i32 m0, s36, 0x6000
	s_nop 0
	global_load_lds_dwordx4 v138, s[44:45]
	s_add_i32 m0, s36, 0x7000
	s_nop 0
	global_load_lds_dwordx4 v139, s[44:45]
	s_add_u32 s30, s30, 0x80
	s_addc_u32 s31, s31, 0
	s_add_u32 s44, s44, 0x80
	s_addc_u32 s45, s45, 0
	v_mfma_f32_16x16x32_bf16 v[62:65], v[188:191], v[148:151], v[62:65]
	v_mfma_f32_16x16x32_bf16 v[58:61], v[192:195], v[148:151], v[58:61]
	v_mfma_f32_16x16x32_bf16 v[54:57], v[208:211], v[148:151], v[54:57]
	v_mfma_f32_16x16x32_bf16 v[50:53], v[212:215], v[148:151], v[50:53]
	v_mfma_f32_16x16x32_bf16 v[46:49], v[188:191], v[152:155], v[46:49]
	v_mfma_f32_16x16x32_bf16 v[42:45], v[192:195], v[152:155], v[42:45]
	v_mfma_f32_16x16x32_bf16 v[38:41], v[208:211], v[152:155], v[38:41]
	v_mfma_f32_16x16x32_bf16 v[34:37], v[212:215], v[152:155], v[34:37]
	v_mfma_f32_16x16x32_bf16 v[30:33], v[188:191], v[156:159], v[30:33]
	v_mfma_f32_16x16x32_bf16 v[26:29], v[192:195], v[156:159], v[26:29]
	v_mfma_f32_16x16x32_bf16 v[22:25], v[208:211], v[156:159], v[22:25]
	v_mfma_f32_16x16x32_bf16 v[18:21], v[212:215], v[156:159], v[18:21]
	v_mfma_f32_16x16x32_bf16 v[14:17], v[188:191], v[160:163], v[14:17]
	v_mfma_f32_16x16x32_bf16 v[10:13], v[192:195], v[160:163], v[10:13]
	v_mfma_f32_16x16x32_bf16 v[6:9], v[208:211], v[160:163], v[6:9]
	v_mfma_f32_16x16x32_bf16 v[2:5], v[212:215], v[160:163], v[2:5]
	v_mfma_f32_16x16x32_bf16 v[66:69], v[188:191], v[164:167], v[66:69]
	v_mfma_f32_16x16x32_bf16 v[70:73], v[192:195], v[164:167], v[70:73]
	v_mfma_f32_16x16x32_bf16 v[74:77], v[208:211], v[164:167], v[74:77]
	v_mfma_f32_16x16x32_bf16 v[78:81], v[212:215], v[164:167], v[78:81]
	v_mfma_f32_16x16x32_bf16 v[82:85], v[188:191], v[168:171], v[82:85]
	v_mfma_f32_16x16x32_bf16 v[86:89], v[192:195], v[168:171], v[86:89]
	v_mfma_f32_16x16x32_bf16 v[90:93], v[208:211], v[168:171], v[90:93]
	v_mfma_f32_16x16x32_bf16 v[94:97], v[212:215], v[168:171], v[94:97]
	v_mfma_f32_16x16x32_bf16 v[98:101], v[188:191], v[174:177], v[98:101]
	v_mfma_f32_16x16x32_bf16 v[102:105], v[192:195], v[174:177], v[102:105]
	v_mfma_f32_16x16x32_bf16 v[106:109], v[208:211], v[174:177], v[106:109]
	v_mfma_f32_16x16x32_bf16 v[110:113], v[212:215], v[174:177], v[110:113]
	v_mfma_f32_16x16x32_bf16 v[114:117], v[188:191], v[182:185], v[114:117]
	v_mfma_f32_16x16x32_bf16 v[118:121], v[192:195], v[182:185], v[118:121]
	v_mfma_f32_16x16x32_bf16 v[122:125], v[208:211], v[182:185], v[122:125]
	v_mfma_f32_16x16x32_bf16 v[126:129], v[212:215], v[182:185], v[126:129]
	s_waitcnt vmcnt(0)
	s_barrier
	ds_read_b128 v[148:151], v140 offset:0
	ds_read_b128 v[152:155], v140 offset:2048
	ds_read_b128 v[156:159], v140 offset:4096
	ds_read_b128 v[160:163], v140 offset:6144
	ds_read_b128 v[164:167], v140 offset:16384
	ds_read_b128 v[168:171], v140 offset:18432
	ds_read_b128 v[174:177], v140 offset:20480
	ds_read_b128 v[182:185], v140 offset:22528
	ds_read_b128 v[188:191], v142 offset:49152
	ds_read_b128 v[192:195], v142 offset:51200
	ds_read_b128 v[208:211], v142 offset:53248
	ds_read_b128 v[212:215], v142 offset:55296
	s_waitcnt lgkmcnt(0)
	v_mfma_f32_16x16x32_bf16 v[62:65], v[188:191], v[148:151], v[62:65]
	v_mfma_f32_16x16x32_bf16 v[58:61], v[192:195], v[148:151], v[58:61]
	v_mfma_f32_16x16x32_bf16 v[54:57], v[208:211], v[148:151], v[54:57]
	v_mfma_f32_16x16x32_bf16 v[50:53], v[212:215], v[148:151], v[50:53]
	v_mfma_f32_16x16x32_bf16 v[46:49], v[188:191], v[152:155], v[46:49]
	v_mfma_f32_16x16x32_bf16 v[42:45], v[192:195], v[152:155], v[42:45]
	v_mfma_f32_16x16x32_bf16 v[38:41], v[208:211], v[152:155], v[38:41]
	v_mfma_f32_16x16x32_bf16 v[34:37], v[212:215], v[152:155], v[34:37]
	v_mfma_f32_16x16x32_bf16 v[30:33], v[188:191], v[156:159], v[30:33]
	v_mfma_f32_16x16x32_bf16 v[26:29], v[192:195], v[156:159], v[26:29]
	v_mfma_f32_16x16x32_bf16 v[22:25], v[208:211], v[156:159], v[22:25]
	v_mfma_f32_16x16x32_bf16 v[18:21], v[212:215], v[156:159], v[18:21]
	v_mfma_f32_16x16x32_bf16 v[14:17], v[188:191], v[160:163], v[14:17]
	v_mfma_f32_16x16x32_bf16 v[10:13], v[192:195], v[160:163], v[10:13]
	v_mfma_f32_16x16x32_bf16 v[6:9], v[208:211], v[160:163], v[6:9]
	v_mfma_f32_16x16x32_bf16 v[2:5], v[212:215], v[160:163], v[2:5]
	v_mfma_f32_16x16x32_bf16 v[66:69], v[188:191], v[164:167], v[66:69]
	v_mfma_f32_16x16x32_bf16 v[70:73], v[192:195], v[164:167], v[70:73]
	v_mfma_f32_16x16x32_bf16 v[74:77], v[208:211], v[164:167], v[74:77]
	v_mfma_f32_16x16x32_bf16 v[78:81], v[212:215], v[164:167], v[78:81]
	v_mfma_f32_16x16x32_bf16 v[82:85], v[188:191], v[168:171], v[82:85]
	v_mfma_f32_16x16x32_bf16 v[86:89], v[192:195], v[168:171], v[86:89]
	v_mfma_f32_16x16x32_bf16 v[90:93], v[208:211], v[168:171], v[90:93]
	v_mfma_f32_16x16x32_bf16 v[94:97], v[212:215], v[168:171], v[94:97]
	v_mfma_f32_16x16x32_bf16 v[98:101], v[188:191], v[174:177], v[98:101]
	v_mfma_f32_16x16x32_bf16 v[102:105], v[192:195], v[174:177], v[102:105]
	v_mfma_f32_16x16x32_bf16 v[106:109], v[208:211], v[174:177], v[106:109]
	v_mfma_f32_16x16x32_bf16 v[110:113], v[212:215], v[174:177], v[110:113]
	v_mfma_f32_16x16x32_bf16 v[114:117], v[188:191], v[182:185], v[114:117]
	v_mfma_f32_16x16x32_bf16 v[118:121], v[192:195], v[182:185], v[118:121]
	v_mfma_f32_16x16x32_bf16 v[122:125], v[208:211], v[182:185], v[122:125]
	v_mfma_f32_16x16x32_bf16 v[126:129], v[212:215], v[182:185], v[126:129]
	ds_read_b128 v[148:151], v141 offset:0
	ds_read_b128 v[152:155], v141 offset:2048
	ds_read_b128 v[156:159], v141 offset:4096
	ds_read_b128 v[160:163], v141 offset:6144
	ds_read_b128 v[164:167], v141 offset:16384
	ds_read_b128 v[168:171], v141 offset:18432
	ds_read_b128 v[174:177], v141 offset:20480
	ds_read_b128 v[182:185], v141 offset:22528
	ds_read_b128 v[188:191], v143 offset:49152
	ds_read_b128 v[192:195], v143 offset:51200
	ds_read_b128 v[208:211], v143 offset:53248
	ds_read_b128 v[212:215], v143 offset:55296
	s_waitcnt lgkmcnt(0)
	v_mfma_f32_16x16x32_bf16 v[62:65], v[188:191], v[148:151], v[62:65]
	v_mfma_f32_16x16x32_bf16 v[58:61], v[192:195], v[148:151], v[58:61]
	v_mfma_f32_16x16x32_bf16 v[54:57], v[208:211], v[148:151], v[54:57]
	v_mfma_f32_16x16x32_bf16 v[50:53], v[212:215], v[148:151], v[50:53]
	v_mfma_f32_16x16x32_bf16 v[46:49], v[188:191], v[152:155], v[46:49]
	v_mfma_f32_16x16x32_bf16 v[42:45], v[192:195], v[152:155], v[42:45]
	v_mfma_f32_16x16x32_bf16 v[38:41], v[208:211], v[152:155], v[38:41]
	v_mfma_f32_16x16x32_bf16 v[34:37], v[212:215], v[152:155], v[34:37]
	v_mfma_f32_16x16x32_bf16 v[30:33], v[188:191], v[156:159], v[30:33]
	v_mfma_f32_16x16x32_bf16 v[26:29], v[192:195], v[156:159], v[26:29]
	v_mfma_f32_16x16x32_bf16 v[22:25], v[208:211], v[156:159], v[22:25]
	v_mfma_f32_16x16x32_bf16 v[18:21], v[212:215], v[156:159], v[18:21]
	v_mfma_f32_16x16x32_bf16 v[14:17], v[188:191], v[160:163], v[14:17]
	v_mfma_f32_16x16x32_bf16 v[10:13], v[192:195], v[160:163], v[10:13]
	v_mfma_f32_16x16x32_bf16 v[6:9], v[208:211], v[160:163], v[6:9]
	v_mfma_f32_16x16x32_bf16 v[2:5], v[212:215], v[160:163], v[2:5]
	v_mfma_f32_16x16x32_bf16 v[66:69], v[188:191], v[164:167], v[66:69]
	v_mfma_f32_16x16x32_bf16 v[70:73], v[192:195], v[164:167], v[70:73]
	v_mfma_f32_16x16x32_bf16 v[74:77], v[208:211], v[164:167], v[74:77]
	v_mfma_f32_16x16x32_bf16 v[78:81], v[212:215], v[164:167], v[78:81]
	v_mfma_f32_16x16x32_bf16 v[82:85], v[188:191], v[168:171], v[82:85]
	v_mfma_f32_16x16x32_bf16 v[86:89], v[192:195], v[168:171], v[86:89]
	v_mfma_f32_16x16x32_bf16 v[90:93], v[208:211], v[168:171], v[90:93]
	v_mfma_f32_16x16x32_bf16 v[94:97], v[212:215], v[168:171], v[94:97]
	v_mfma_f32_16x16x32_bf16 v[98:101], v[188:191], v[174:177], v[98:101]
	v_mfma_f32_16x16x32_bf16 v[102:105], v[192:195], v[174:177], v[102:105]
	v_mfma_f32_16x16x32_bf16 v[106:109], v[208:211], v[174:177], v[106:109]
	v_mfma_f32_16x16x32_bf16 v[110:113], v[212:215], v[174:177], v[110:113]
	v_mfma_f32_16x16x32_bf16 v[114:117], v[188:191], v[182:185], v[114:117]
	v_mfma_f32_16x16x32_bf16 v[118:121], v[192:195], v[182:185], v[118:121]
	v_mfma_f32_16x16x32_bf16 v[122:125], v[208:211], v[182:185], v[122:125]
	v_mfma_f32_16x16x32_bf16 v[126:129], v[212:215], v[182:185], v[126:129]
	v_lshrrev_b32_e32 v144, 7, v196
	v_and_b32_e32 v145, 15, v196
	v_lshl_or_b32 v144, v144, 6, v145
	v_lshlrev_b32_e32 v144, 12, v144
	v_bfe_u32 v145, v196, 6, 1
	v_bfe_u32 v146, v196, 4, 2
	v_lshlrev_b32_e32 v145, 8, v145
	v_lshl_or_b32 v145, v146, 4, v145
	v_add_u32_e32 v136, v144, v145
	v_add_u32_e32 v137, 0x10000, v136
	v_add_u32_e32 v138, 0x20000, v136
	v_add_u32_e32 v139, 0x30000, v136
	s_nop 7
	s_nop 7
	s_nop 7
	global_load_dwordx4 v[148:151], v136, s[40:41] offset:0
	global_load_dwordx4 v[152:155], v136, s[40:41] offset:64
	global_load_dwordx4 v[156:159], v136, s[40:41] offset:128
	global_load_dwordx4 v[160:163], v136, s[40:41] offset:192
	global_load_dwordx4 v[164:167], v137, s[40:41] offset:0
	global_load_dwordx4 v[168:171], v137, s[40:41] offset:64
	global_load_dwordx4 v[174:177], v137, s[40:41] offset:128
	global_load_dwordx4 v[182:185], v137, s[40:41] offset:192
	global_load_dwordx4 v[188:191], v138, s[40:41] offset:0
	global_load_dwordx4 v[192:195], v138, s[40:41] offset:64
	global_load_dwordx4 v[208:211], v138, s[40:41] offset:128
	global_load_dwordx4 v[212:215], v138, s[40:41] offset:192
	global_load_dwordx4 v[216:219], v139, s[40:41] offset:0
	global_load_dwordx4 v[220:223], v139, s[40:41] offset:64
	global_load_dwordx4 v[242:245], v139, s[40:41] offset:128
	global_load_dwordx4 v[144:147], v139, s[40:41] offset:192
	s_waitcnt vmcnt(0)
	v_pk_add_f32 v[62:63], v[62:63], v[148:149]
	v_pk_add_f32 v[64:65], v[64:65], v[150:151]
	v_pk_add_f32 v[58:59], v[58:59], v[152:153]
	v_pk_add_f32 v[60:61], v[60:61], v[154:155]
	v_pk_add_f32 v[54:55], v[54:55], v[156:157]
	v_pk_add_f32 v[56:57], v[56:57], v[158:159]
	v_pk_add_f32 v[50:51], v[50:51], v[160:161]
	v_pk_add_f32 v[52:53], v[52:53], v[162:163]
	v_pk_add_f32 v[46:47], v[46:47], v[164:165]
	v_pk_add_f32 v[48:49], v[48:49], v[166:167]
	v_pk_add_f32 v[42:43], v[42:43], v[168:169]
	v_pk_add_f32 v[44:45], v[44:45], v[170:171]
	v_pk_add_f32 v[38:39], v[38:39], v[174:175]
	v_pk_add_f32 v[40:41], v[40:41], v[176:177]
	v_pk_add_f32 v[34:35], v[34:35], v[182:183]
	v_pk_add_f32 v[36:37], v[36:37], v[184:185]
	v_pk_add_f32 v[30:31], v[30:31], v[188:189]
	v_pk_add_f32 v[32:33], v[32:33], v[190:191]
	v_pk_add_f32 v[26:27], v[26:27], v[192:193]
	v_pk_add_f32 v[28:29], v[28:29], v[194:195]
	v_pk_add_f32 v[22:23], v[22:23], v[208:209]
	v_pk_add_f32 v[24:25], v[24:25], v[210:211]
	v_pk_add_f32 v[18:19], v[18:19], v[212:213]
	v_pk_add_f32 v[20:21], v[20:21], v[214:215]
	v_pk_add_f32 v[14:15], v[14:15], v[216:217]
	v_pk_add_f32 v[16:17], v[16:17], v[218:219]
	v_pk_add_f32 v[10:11], v[10:11], v[220:221]
	v_pk_add_f32 v[12:13], v[12:13], v[222:223]
	v_pk_add_f32 v[6:7], v[6:7], v[242:243]
	v_pk_add_f32 v[8:9], v[8:9], v[244:245]
	v_pk_add_f32 v[2:3], v[2:3], v[144:145]
	v_pk_add_f32 v[4:5], v[4:5], v[146:147]
	global_load_dwordx4 v[148:151], v136, s[42:43] offset:0
	global_load_dwordx4 v[152:155], v136, s[42:43] offset:64
	global_load_dwordx4 v[156:159], v136, s[42:43] offset:128
	global_load_dwordx4 v[160:163], v136, s[42:43] offset:192
	global_load_dwordx4 v[164:167], v137, s[42:43] offset:0
	global_load_dwordx4 v[168:171], v137, s[42:43] offset:64
	global_load_dwordx4 v[174:177], v137, s[42:43] offset:128
	global_load_dwordx4 v[182:185], v137, s[42:43] offset:192
	global_load_dwordx4 v[188:191], v138, s[42:43] offset:0
	global_load_dwordx4 v[192:195], v138, s[42:43] offset:64
	global_load_dwordx4 v[208:211], v138, s[42:43] offset:128
	global_load_dwordx4 v[212:215], v138, s[42:43] offset:192
	global_load_dwordx4 v[216:219], v139, s[42:43] offset:0
	global_load_dwordx4 v[220:223], v139, s[42:43] offset:64
	global_load_dwordx4 v[242:245], v139, s[42:43] offset:128
	global_load_dwordx4 v[144:147], v139, s[42:43] offset:192
	global_store_dwordx4 v136, v[62:65], s[40:41] offset:0
	global_store_dwordx4 v136, v[58:61], s[40:41] offset:64
	global_store_dwordx4 v136, v[54:57], s[40:41] offset:128
	global_store_dwordx4 v136, v[50:53], s[40:41] offset:192
	global_store_dwordx4 v137, v[46:49], s[40:41] offset:0
	global_store_dwordx4 v137, v[42:45], s[40:41] offset:64
	global_store_dwordx4 v137, v[38:41], s[40:41] offset:128
	global_store_dwordx4 v137, v[34:37], s[40:41] offset:192
	global_store_dwordx4 v138, v[30:33], s[40:41] offset:0
	global_store_dwordx4 v138, v[26:29], s[40:41] offset:64
	global_store_dwordx4 v138, v[22:25], s[40:41] offset:128
	global_store_dwordx4 v138, v[18:21], s[40:41] offset:192
	global_store_dwordx4 v139, v[14:17], s[40:41] offset:0
	global_store_dwordx4 v139, v[10:13], s[40:41] offset:64
	global_store_dwordx4 v139, v[6:9], s[40:41] offset:128
	global_store_dwordx4 v139, v[2:5], s[40:41] offset:192
	s_waitcnt vmcnt(0)
	v_pk_add_f32 v[66:67], v[66:67], v[148:149]
	v_pk_add_f32 v[68:69], v[68:69], v[150:151]
	v_pk_add_f32 v[70:71], v[70:71], v[152:153]
	v_pk_add_f32 v[72:73], v[72:73], v[154:155]
	v_pk_add_f32 v[74:75], v[74:75], v[156:157]
	v_pk_add_f32 v[76:77], v[76:77], v[158:159]
	v_pk_add_f32 v[78:79], v[78:79], v[160:161]
	v_pk_add_f32 v[80:81], v[80:81], v[162:163]
	v_pk_add_f32 v[82:83], v[82:83], v[164:165]
	v_pk_add_f32 v[84:85], v[84:85], v[166:167]
	v_pk_add_f32 v[86:87], v[86:87], v[168:169]
	v_pk_add_f32 v[88:89], v[88:89], v[170:171]
	v_pk_add_f32 v[90:91], v[90:91], v[174:175]
	v_pk_add_f32 v[92:93], v[92:93], v[176:177]
	v_pk_add_f32 v[94:95], v[94:95], v[182:183]
	v_pk_add_f32 v[96:97], v[96:97], v[184:185]
	v_pk_add_f32 v[98:99], v[98:99], v[188:189]
	v_pk_add_f32 v[100:101], v[100:101], v[190:191]
	v_pk_add_f32 v[102:103], v[102:103], v[192:193]
	v_pk_add_f32 v[104:105], v[104:105], v[194:195]
	v_pk_add_f32 v[106:107], v[106:107], v[208:209]
	v_pk_add_f32 v[108:109], v[108:109], v[210:211]
	v_pk_add_f32 v[110:111], v[110:111], v[212:213]
	v_pk_add_f32 v[112:113], v[112:113], v[214:215]
	v_pk_add_f32 v[114:115], v[114:115], v[216:217]
	v_pk_add_f32 v[116:117], v[116:117], v[218:219]
	v_pk_add_f32 v[118:119], v[118:119], v[220:221]
	v_pk_add_f32 v[120:121], v[120:121], v[222:223]
	v_pk_add_f32 v[122:123], v[122:123], v[242:243]
	v_pk_add_f32 v[124:125], v[124:125], v[244:245]
	v_pk_add_f32 v[126:127], v[126:127], v[144:145]
	v_pk_add_f32 v[128:129], v[128:129], v[146:147]
	global_store_dwordx4 v136, v[66:69], s[42:43] offset:0
	global_store_dwordx4 v136, v[70:73], s[42:43] offset:64
	global_store_dwordx4 v136, v[74:77], s[42:43] offset:128
	global_store_dwordx4 v136, v[78:81], s[42:43] offset:192
	global_store_dwordx4 v137, v[82:85], s[42:43] offset:0
	global_store_dwordx4 v137, v[86:89], s[42:43] offset:64
	global_store_dwordx4 v137, v[90:93], s[42:43] offset:128
	global_store_dwordx4 v137, v[94:97], s[42:43] offset:192
	global_store_dwordx4 v138, v[98:101], s[42:43] offset:0
	global_store_dwordx4 v138, v[102:105], s[42:43] offset:64
	global_store_dwordx4 v138, v[106:109], s[42:43] offset:128
	global_store_dwordx4 v138, v[110:113], s[42:43] offset:192
	global_store_dwordx4 v139, v[114:117], s[42:43] offset:0
	global_store_dwordx4 v139, v[118:121], s[42:43] offset:64
	global_store_dwordx4 v139, v[122:125], s[42:43] offset:128
	global_store_dwordx4 v139, v[126:129], s[42:43] offset:192
	s_branch .LBB0_2421
